# counted waits at the GEMM load-to-MFMA transition: head MFMAs wait only for their own LDS fragments; full lgkmcnt(0) and the LDS-DMA vmcnt wait moved to just before the barrier
# baseline (speedup 1.0000x reference)
.LBB0_168:
	s_add_u32 s46, s66, 0xfff80080
	s_addc_u32 s47, s67, -1
	s_add_i32 s62, 0, 0x10000
	s_cmp_eq_u32 s82, 28
	s_cselect_b32 s69, s17, s47
	s_cselect_b32 s68, s65, s46
	v_add_u32_e32 v143, s62, v140
	s_cselect_b32 s61, s13, s81
	s_cselect_b32 s60, s79, s80
	s_add_i32 s63, 0, 0x14000
	ds_read_b128 v[144:147], v143
	ds_read_b128 v[148:151], v143 offset:1024
	ds_read_b128 v[152:155], v143 offset:2048
	ds_read_b128 v[156:159], v143 offset:3072
	v_add_u32_e32 v143, s63, v140
	ds_read_b128 v[160:163], v143
	ds_read_b128 v[178:181], v143 offset:1024
	ds_read_b128 v[182:185], v143 offset:2048
	ds_read_b128 v[186:189], v143 offset:3072
	v_lshl_add_u64 v[164:165], s[66:67], 0, v[136:137]
	s_add_i32 m0, s19, 0xc000
	ds_read_b128 v[206:209], v142
	ds_read_b128 v[210:213], v142 offset:1024
	ds_read_b128 v[214:217], v142 offset:2048
	ds_read_b128 v[218:221], v142 offset:3072
	ds_read_b128 v[222:225], v142 offset:4096
	ds_read_b128 v[226:229], v142 offset:5120
	ds_read_b128 v[230:233], v142 offset:6144
	ds_read_b128 v[234:237], v142 offset:7168
	global_load_lds_dwordx4 v[164:165], off
	v_lshl_add_u64 v[164:165], s[66:67], 0, v[138:139]
	s_add_i32 m0, s19, 0xe000
	s_nop 0
	global_load_lds_dwordx4 v[164:165], off
	s_setprio 1
	s_waitcnt lgkmcnt(7)
	v_mfma_f32_16x16x32_bf16 v[126:129], v[144:147], v[206:209], v[126:129]
	v_mfma_f32_16x16x32_bf16 v[122:125], v[152:155], v[206:209], v[122:125]
	s_waitcnt lgkmcnt(5)
	v_mfma_f32_16x16x32_bf16 v[118:121], v[144:147], v[214:217], v[118:121]
	v_mfma_f32_16x16x32_bf16 v[114:117], v[152:155], v[214:217], v[114:117]
	s_waitcnt vmcnt(8)
	s_waitcnt lgkmcnt(0)
	s_barrier
	v_mfma_f32_16x16x32_bf16 v[102:105], v[144:147], v[222:225], v[102:105]
	v_mfma_f32_16x16x32_bf16 v[98:101], v[152:155], v[222:225], v[98:101]
	v_mfma_f32_16x16x32_bf16 v[86:89], v[144:147], v[230:233], v[86:89]
	v_mfma_f32_16x16x32_bf16 v[82:85], v[152:155], v[230:233], v[82:85]
	v_mfma_f32_16x16x32_bf16 v[126:129], v[148:151], v[210:213], v[126:129]
	v_mfma_f32_16x16x32_bf16 v[122:125], v[156:159], v[210:213], v[122:125]
	v_mfma_f32_16x16x32_bf16 v[118:121], v[148:151], v[218:221], v[118:121]
	v_mfma_f32_16x16x32_bf16 v[114:117], v[156:159], v[218:221], v[114:117]
	v_mfma_f32_16x16x32_bf16 v[102:105], v[148:151], v[226:229], v[102:105]
	v_mfma_f32_16x16x32_bf16 v[98:101], v[156:159], v[226:229], v[98:101]
	v_mfma_f32_16x16x32_bf16 v[86:89], v[148:151], v[234:237], v[86:89]
	v_mfma_f32_16x16x32_bf16 v[82:85], v[156:159], v[234:237], v[82:85]
	s_setprio 0
	s_setprio 1
	v_mfma_f32_16x16x32_bf16 v[110:113], v[160:163], v[206:209], v[110:113]
	v_mfma_f32_16x16x32_bf16 v[106:109], v[182:185], v[206:209], v[106:109]
	v_mfma_f32_16x16x32_bf16 v[94:97], v[160:163], v[214:217], v[94:97]
	v_mfma_f32_16x16x32_bf16 v[90:93], v[182:185], v[214:217], v[90:93]
	v_mfma_f32_16x16x32_bf16 v[78:81], v[160:163], v[222:225], v[78:81]
	v_mfma_f32_16x16x32_bf16 v[74:77], v[182:185], v[222:225], v[74:77]
	v_mfma_f32_16x16x32_bf16 v[70:73], v[160:163], v[230:233], v[70:73]
	v_mfma_f32_16x16x32_bf16 v[66:69], v[182:185], v[230:233], v[66:69]
	v_mfma_f32_16x16x32_bf16 v[110:113], v[178:181], v[210:213], v[110:113]
	v_mfma_f32_16x16x32_bf16 v[106:109], v[186:189], v[210:213], v[106:109]
	v_mfma_f32_16x16x32_bf16 v[94:97], v[178:181], v[218:221], v[94:97]
	v_mfma_f32_16x16x32_bf16 v[90:93], v[186:189], v[218:221], v[90:93]
	v_mfma_f32_16x16x32_bf16 v[78:81], v[178:181], v[226:229], v[78:81]
	v_mfma_f32_16x16x32_bf16 v[74:77], v[186:189], v[226:229], v[74:77]
	v_mfma_f32_16x16x32_bf16 v[70:73], v[178:181], v[234:237], v[70:73]
	v_mfma_f32_16x16x32_bf16 v[66:69], v[186:189], v[234:237], v[66:69]
	s_barrier
	s_setprio 0
	s_add_i32 s46, s62, s71
	v_lshl_add_u64 v[164:165], s[60:61], 0, v[166:167]
	s_mov_b32 m0, s46
	ds_read_b128 v[206:209], v142 offset:16384
	ds_read_b128 v[210:213], v142 offset:17408
	ds_read_b128 v[214:217], v142 offset:18432
	ds_read_b128 v[218:221], v142 offset:19456
	ds_read_b128 v[222:225], v142 offset:20480
	ds_read_b128 v[226:229], v142 offset:21504
	ds_read_b128 v[230:233], v142 offset:22528
	ds_read_b128 v[234:237], v142 offset:23552
	global_load_lds_dwordx4 v[164:165], off
	s_add_i32 m0, s46, 0x2000
	s_add_u32 s46, s60, 0x80000
	v_lshl_add_u64 v[242:243], s[60:61], 0, v[130:131]
	s_addc_u32 s47, s61, 0
	s_add_i32 s62, s63, s71
	global_load_lds_dwordx4 v[242:243], off
	v_lshl_add_u64 v[244:245], s[46:47], 0, v[166:167]
	s_mov_b32 m0, s62
	v_lshl_add_u64 v[246:247], s[68:69], 0, v[132:133]
	global_load_lds_dwordx4 v[244:245], off
	v_lshl_add_u64 v[244:245], s[46:47], 0, v[130:131]
	s_add_i32 m0, s62, 0x2000
	s_nop 0
	global_load_lds_dwordx4 v[244:245], off
	v_lshl_add_u64 v[244:245], s[68:69], 0, v[134:135]
	s_mov_b32 m0, s19
	s_nop 0
	global_load_lds_dwordx4 v[244:245], off
	s_mov_b32 m0, s73
	s_nop 0
	global_load_lds_dwordx4 v[246:247], off
	s_setprio 1
	s_waitcnt lgkmcnt(7)
	v_mfma_f32_16x16x32_bf16 v[62:65], v[144:147], v[206:209], v[62:65]
	v_mfma_f32_16x16x32_bf16 v[58:61], v[152:155], v[206:209], v[58:61]
	s_waitcnt lgkmcnt(5)
	v_mfma_f32_16x16x32_bf16 v[54:57], v[144:147], v[214:217], v[54:57]
	v_mfma_f32_16x16x32_bf16 v[50:53], v[152:155], v[214:217], v[50:53]
	s_waitcnt vmcnt(8)
	s_waitcnt lgkmcnt(0)
	s_barrier
	v_mfma_f32_16x16x32_bf16 v[38:41], v[144:147], v[222:225], v[38:41]
	v_mfma_f32_16x16x32_bf16 v[34:37], v[152:155], v[222:225], v[34:37]
	v_mfma_f32_16x16x32_bf16 v[22:25], v[144:147], v[230:233], v[22:25]
	v_mfma_f32_16x16x32_bf16 v[18:21], v[152:155], v[230:233], v[18:21]
	v_mfma_f32_16x16x32_bf16 v[62:65], v[148:151], v[210:213], v[62:65]
	v_mfma_f32_16x16x32_bf16 v[58:61], v[156:159], v[210:213], v[58:61]
	v_mfma_f32_16x16x32_bf16 v[54:57], v[148:151], v[218:221], v[54:57]
	v_mfma_f32_16x16x32_bf16 v[50:53], v[156:159], v[218:221], v[50:53]
	v_mfma_f32_16x16x32_bf16 v[38:41], v[148:151], v[226:229], v[38:41]
	v_mfma_f32_16x16x32_bf16 v[34:37], v[156:159], v[226:229], v[34:37]
	v_mfma_f32_16x16x32_bf16 v[22:25], v[148:151], v[234:237], v[22:25]
	v_mfma_f32_16x16x32_bf16 v[18:21], v[156:159], v[234:237], v[18:21]
	s_setprio 0
	s_setprio 1
	v_mfma_f32_16x16x32_bf16 v[46:49], v[160:163], v[206:209], v[46:49]
	v_mfma_f32_16x16x32_bf16 v[42:45], v[182:185], v[206:209], v[42:45]
	v_mfma_f32_16x16x32_bf16 v[30:33], v[160:163], v[214:217], v[30:33]
	v_mfma_f32_16x16x32_bf16 v[26:29], v[182:185], v[214:217], v[26:29]
	v_mfma_f32_16x16x32_bf16 v[14:17], v[160:163], v[222:225], v[14:17]
	v_mfma_f32_16x16x32_bf16 v[10:13], v[182:185], v[222:225], v[10:13]
	v_mfma_f32_16x16x32_bf16 v[6:9], v[160:163], v[230:233], v[6:9]
	v_mfma_f32_16x16x32_bf16 v[2:5], v[182:185], v[230:233], v[2:5]
	v_mfma_f32_16x16x32_bf16 v[46:49], v[178:181], v[210:213], v[46:49]
	v_mfma_f32_16x16x32_bf16 v[42:45], v[186:189], v[210:213], v[42:45]
	v_mfma_f32_16x16x32_bf16 v[30:33], v[178:181], v[218:221], v[30:33]
	v_mfma_f32_16x16x32_bf16 v[26:29], v[186:189], v[218:221], v[26:29]
	v_mfma_f32_16x16x32_bf16 v[14:17], v[178:181], v[226:229], v[14:17]
	v_mfma_f32_16x16x32_bf16 v[10:13], v[186:189], v[226:229], v[10:13]
	v_mfma_f32_16x16x32_bf16 v[6:9], v[178:181], v[234:237], v[6:9]
	v_mfma_f32_16x16x32_bf16 v[2:5], v[186:189], v[234:237], v[2:5]
	s_barrier
	s_setprio 0
	s_add_i32 s62, 0, 0x18000
	v_add_u32_e32 v143, s62, v140
	s_add_i32 s63, 0, 0x1c000
	ds_read_b128 v[144:147], v143
	ds_read_b128 v[148:151], v143 offset:1024
	ds_read_b128 v[152:155], v143 offset:2048
	ds_read_b128 v[156:159], v143 offset:3072
	v_add_u32_e32 v143, s63, v140
	ds_read_b128 v[160:163], v143
	ds_read_b128 v[178:181], v143 offset:1024
	ds_read_b128 v[182:185], v143 offset:2048
	ds_read_b128 v[186:189], v143 offset:3072
	s_add_u32 s46, s68, 0x80000
	s_addc_u32 s47, s69, 0
	s_mov_b32 m0, s74
	v_lshl_add_u64 v[248:249], s[46:47], 0, v[134:135]
	ds_read_b128 v[206:209], v142 offset:32768
	ds_read_b128 v[210:213], v142 offset:33792
	ds_read_b128 v[214:217], v142 offset:34816
	ds_read_b128 v[218:221], v142 offset:35840
	ds_read_b128 v[222:225], v142 offset:36864
	ds_read_b128 v[226:229], v142 offset:37888
	ds_read_b128 v[230:233], v142 offset:38912
	ds_read_b128 v[234:237], v142 offset:39936
	global_load_lds_dwordx4 v[248:249], off
	v_lshl_add_u64 v[248:249], s[46:47], 0, v[132:133]
	s_mov_b32 m0, s75
	s_nop 0
	global_load_lds_dwordx4 v[248:249], off
	s_setprio 1
	s_waitcnt lgkmcnt(7)
	v_mfma_f32_16x16x32_bf16 v[126:129], v[144:147], v[206:209], v[126:129]
	v_mfma_f32_16x16x32_bf16 v[122:125], v[152:155], v[206:209], v[122:125]
	s_waitcnt lgkmcnt(5)
	v_mfma_f32_16x16x32_bf16 v[118:121], v[144:147], v[214:217], v[118:121]
	v_mfma_f32_16x16x32_bf16 v[114:117], v[152:155], v[214:217], v[114:117]
	s_waitcnt vmcnt(8)
	s_waitcnt lgkmcnt(0)
	s_barrier
	v_mfma_f32_16x16x32_bf16 v[102:105], v[144:147], v[222:225], v[102:105]
	v_mfma_f32_16x16x32_bf16 v[98:101], v[152:155], v[222:225], v[98:101]
	v_mfma_f32_16x16x32_bf16 v[86:89], v[144:147], v[230:233], v[86:89]
	v_mfma_f32_16x16x32_bf16 v[82:85], v[152:155], v[230:233], v[82:85]
	v_mfma_f32_16x16x32_bf16 v[126:129], v[148:151], v[210:213], v[126:129]
	v_mfma_f32_16x16x32_bf16 v[122:125], v[156:159], v[210:213], v[122:125]
	v_mfma_f32_16x16x32_bf16 v[118:121], v[148:151], v[218:221], v[118:121]
	v_mfma_f32_16x16x32_bf16 v[114:117], v[156:159], v[218:221], v[114:117]
	v_mfma_f32_16x16x32_bf16 v[102:105], v[148:151], v[226:229], v[102:105]
	v_mfma_f32_16x16x32_bf16 v[98:101], v[156:159], v[226:229], v[98:101]
	v_mfma_f32_16x16x32_bf16 v[86:89], v[148:151], v[234:237], v[86:89]
	v_mfma_f32_16x16x32_bf16 v[82:85], v[156:159], v[234:237], v[82:85]
	s_setprio 0
	s_setprio 1
	v_mfma_f32_16x16x32_bf16 v[110:113], v[160:163], v[206:209], v[110:113]
	v_mfma_f32_16x16x32_bf16 v[106:109], v[182:185], v[206:209], v[106:109]
	v_mfma_f32_16x16x32_bf16 v[94:97], v[160:163], v[214:217], v[94:97]
	v_mfma_f32_16x16x32_bf16 v[90:93], v[182:185], v[214:217], v[90:93]
	v_mfma_f32_16x16x32_bf16 v[78:81], v[160:163], v[222:225], v[78:81]
	v_mfma_f32_16x16x32_bf16 v[74:77], v[182:185], v[222:225], v[74:77]
	v_mfma_f32_16x16x32_bf16 v[70:73], v[160:163], v[230:233], v[70:73]
	v_mfma_f32_16x16x32_bf16 v[66:69], v[182:185], v[230:233], v[66:69]
	v_mfma_f32_16x16x32_bf16 v[110:113], v[178:181], v[210:213], v[110:113]
	v_mfma_f32_16x16x32_bf16 v[106:109], v[186:189], v[210:213], v[106:109]
	v_mfma_f32_16x16x32_bf16 v[94:97], v[178:181], v[218:221], v[94:97]
	v_mfma_f32_16x16x32_bf16 v[90:93], v[186:189], v[218:221], v[90:93]
	v_mfma_f32_16x16x32_bf16 v[78:81], v[178:181], v[226:229], v[78:81]
	v_mfma_f32_16x16x32_bf16 v[74:77], v[186:189], v[226:229], v[74:77]
	v_mfma_f32_16x16x32_bf16 v[70:73], v[178:181], v[234:237], v[70:73]
	v_mfma_f32_16x16x32_bf16 v[66:69], v[186:189], v[234:237], v[66:69]
	s_barrier
	s_setprio 0
	s_add_i32 s46, s62, s71
	v_lshl_add_u64 v[164:165], v[164:165], 0, s[42:43]
	s_mov_b32 m0, s46
	ds_read_b128 v[206:209], v142 offset:49152
	ds_read_b128 v[210:213], v142 offset:50176
	ds_read_b128 v[214:217], v142 offset:51200
	ds_read_b128 v[218:221], v142 offset:52224
	ds_read_b128 v[222:225], v142 offset:53248
	ds_read_b128 v[226:229], v142 offset:54272
	ds_read_b128 v[230:233], v142 offset:55296
	ds_read_b128 v[234:237], v142 offset:56320
	global_load_lds_dwordx4 v[164:165], off
	s_add_i32 m0, s46, 0x2000
	s_add_u32 s46, s60, 0x80080
	v_lshl_add_u64 v[164:165], v[242:243], 0, s[42:43]
	s_addc_u32 s47, s61, 0
	s_add_i32 s60, s63, s71
	global_load_lds_dwordx4 v[164:165], off
	v_lshl_add_u64 v[164:165], s[46:47], 0, v[166:167]
	s_mov_b32 m0, s60
	s_nop 0
	global_load_lds_dwordx4 v[164:165], off
	v_lshl_add_u64 v[164:165], s[46:47], 0, v[130:131]
	s_add_i32 m0, s60, 0x2000
	s_nop 0
	global_load_lds_dwordx4 v[164:165], off
	v_lshl_add_u64 v[164:165], v[244:245], 0, s[42:43]
	s_mov_b32 m0, s76
	s_nop 0
	global_load_lds_dwordx4 v[164:165], off
	v_lshl_add_u64 v[164:165], v[246:247], 0, s[42:43]
	s_mov_b32 m0, s77
	s_nop 0
	global_load_lds_dwordx4 v[164:165], off
	s_setprio 1
	s_waitcnt lgkmcnt(7)
	v_mfma_f32_16x16x32_bf16 v[62:65], v[144:147], v[206:209], v[62:65]
	v_mfma_f32_16x16x32_bf16 v[58:61], v[152:155], v[206:209], v[58:61]
	s_waitcnt lgkmcnt(5)
	v_mfma_f32_16x16x32_bf16 v[54:57], v[144:147], v[214:217], v[54:57]
	v_mfma_f32_16x16x32_bf16 v[50:53], v[152:155], v[214:217], v[50:53]
	s_waitcnt vmcnt(8)
	s_waitcnt lgkmcnt(0)
	s_barrier
	v_mfma_f32_16x16x32_bf16 v[38:41], v[144:147], v[222:225], v[38:41]
	v_mfma_f32_16x16x32_bf16 v[34:37], v[152:155], v[222:225], v[34:37]
	v_mfma_f32_16x16x32_bf16 v[22:25], v[144:147], v[230:233], v[22:25]
	v_mfma_f32_16x16x32_bf16 v[18:21], v[152:155], v[230:233], v[18:21]
	v_mfma_f32_16x16x32_bf16 v[62:65], v[148:151], v[210:213], v[62:65]
	v_mfma_f32_16x16x32_bf16 v[58:61], v[156:159], v[210:213], v[58:61]
	v_mfma_f32_16x16x32_bf16 v[54:57], v[148:151], v[218:221], v[54:57]
	v_mfma_f32_16x16x32_bf16 v[50:53], v[156:159], v[218:221], v[50:53]
	v_mfma_f32_16x16x32_bf16 v[38:41], v[148:151], v[226:229], v[38:41]
	v_mfma_f32_16x16x32_bf16 v[34:37], v[156:159], v[226:229], v[34:37]
	v_mfma_f32_16x16x32_bf16 v[22:25], v[148:151], v[234:237], v[22:25]
	v_mfma_f32_16x16x32_bf16 v[18:21], v[156:159], v[234:237], v[18:21]
	s_setprio 0
	s_setprio 1
	v_mfma_f32_16x16x32_bf16 v[46:49], v[160:163], v[206:209], v[46:49]
	v_mfma_f32_16x16x32_bf16 v[42:45], v[182:185], v[206:209], v[42:45]
	v_mfma_f32_16x16x32_bf16 v[30:33], v[160:163], v[214:217], v[30:33]
	v_mfma_f32_16x16x32_bf16 v[26:29], v[182:185], v[214:217], v[26:29]
	v_mfma_f32_16x16x32_bf16 v[14:17], v[160:163], v[222:225], v[14:17]
	v_mfma_f32_16x16x32_bf16 v[10:13], v[182:185], v[222:225], v[10:13]
	v_mfma_f32_16x16x32_bf16 v[6:9], v[160:163], v[230:233], v[6:9]
	v_mfma_f32_16x16x32_bf16 v[2:5], v[182:185], v[230:233], v[2:5]
	v_mfma_f32_16x16x32_bf16 v[46:49], v[178:181], v[210:213], v[46:49]
	v_mfma_f32_16x16x32_bf16 v[42:45], v[186:189], v[210:213], v[42:45]
	v_mfma_f32_16x16x32_bf16 v[30:33], v[178:181], v[218:221], v[30:33]
	v_mfma_f32_16x16x32_bf16 v[26:29], v[186:189], v[218:221], v[26:29]
	v_mfma_f32_16x16x32_bf16 v[14:17], v[178:181], v[226:229], v[14:17]
	v_mfma_f32_16x16x32_bf16 v[10:13], v[186:189], v[226:229], v[10:13]
	v_mfma_f32_16x16x32_bf16 v[6:9], v[178:181], v[234:237], v[6:9]
	v_mfma_f32_16x16x32_bf16 v[2:5], v[186:189], v[234:237], v[2:5]
	s_barrier
	s_setprio 0
	s_add_i32 s82, s82, 2
	s_add_u32 s66, s66, 0x100
	s_addc_u32 s67, s67, 0
	s_add_u32 s80, s80, 0x100
	s_addc_u32 s81, s81, 0
	s_cmp_gt_u32 s82, 29
	s_cbranch_scc0 .LBB0_168
	s_and_b64 vcc, exec, s[10:11]
	s_cbranch_vccz .LBB0_171
	s_barrier

.LBB0_426:
	s_add_u32 s46, s66, 0xfffe0080
	s_addc_u32 s47, s67, -1
	s_add_i32 s62, 0, 0x10000
	s_cmp_eq_u32 s84, 4
	s_cselect_b32 s69, s19, s47
	s_cselect_b32 s68, s80, s46
	v_add_u32_e32 v143, s62, v140
	s_cselect_b32 s61, s17, s83
	s_cselect_b32 s60, s81, s82
	s_add_i32 s63, 0, 0x14000
	ds_read_b128 v[144:147], v143
	ds_read_b128 v[148:151], v143 offset:1024
	ds_read_b128 v[152:155], v143 offset:2048
	ds_read_b128 v[156:159], v143 offset:3072
	v_add_u32_e32 v143, s63, v140
	ds_read_b128 v[160:163], v143
	ds_read_b128 v[178:181], v143 offset:1024
	ds_read_b128 v[182:185], v143 offset:2048
	ds_read_b128 v[186:189], v143 offset:3072
	v_lshl_add_u64 v[164:165], s[66:67], 0, v[136:137]
	s_add_i32 m0, s11, 0xc000
	ds_read_b128 v[206:209], v142
	ds_read_b128 v[210:213], v142 offset:1024
	ds_read_b128 v[214:217], v142 offset:2048
	ds_read_b128 v[218:221], v142 offset:3072
	ds_read_b128 v[222:225], v142 offset:4096
	ds_read_b128 v[226:229], v142 offset:5120
	ds_read_b128 v[230:233], v142 offset:6144
	ds_read_b128 v[234:237], v142 offset:7168
	global_load_lds_dwordx4 v[164:165], off
	v_lshl_add_u64 v[164:165], s[66:67], 0, v[138:139]
	s_add_i32 m0, s11, 0xe000
	s_nop 0
	global_load_lds_dwordx4 v[164:165], off
	s_setprio 1
	s_waitcnt lgkmcnt(7)
	v_mfma_f32_16x16x32_bf16 v[126:129], v[144:147], v[206:209], v[126:129]
	v_mfma_f32_16x16x32_bf16 v[122:125], v[152:155], v[206:209], v[122:125]
	s_waitcnt lgkmcnt(5)
	v_mfma_f32_16x16x32_bf16 v[118:121], v[144:147], v[214:217], v[118:121]
	v_mfma_f32_16x16x32_bf16 v[114:117], v[152:155], v[214:217], v[114:117]
	s_waitcnt vmcnt(8)
	s_waitcnt lgkmcnt(0)
	s_barrier
	v_mfma_f32_16x16x32_bf16 v[102:105], v[144:147], v[222:225], v[102:105]
	v_mfma_f32_16x16x32_bf16 v[98:101], v[152:155], v[222:225], v[98:101]
	v_mfma_f32_16x16x32_bf16 v[86:89], v[144:147], v[230:233], v[86:89]
	v_mfma_f32_16x16x32_bf16 v[82:85], v[152:155], v[230:233], v[82:85]
	v_mfma_f32_16x16x32_bf16 v[126:129], v[148:151], v[210:213], v[126:129]
	v_mfma_f32_16x16x32_bf16 v[122:125], v[156:159], v[210:213], v[122:125]
	v_mfma_f32_16x16x32_bf16 v[118:121], v[148:151], v[218:221], v[118:121]
	v_mfma_f32_16x16x32_bf16 v[114:117], v[156:159], v[218:221], v[114:117]
	v_mfma_f32_16x16x32_bf16 v[102:105], v[148:151], v[226:229], v[102:105]
	v_mfma_f32_16x16x32_bf16 v[98:101], v[156:159], v[226:229], v[98:101]
	v_mfma_f32_16x16x32_bf16 v[86:89], v[148:151], v[234:237], v[86:89]
	v_mfma_f32_16x16x32_bf16 v[82:85], v[156:159], v[234:237], v[82:85]
	s_setprio 0
	s_setprio 1
	v_mfma_f32_16x16x32_bf16 v[110:113], v[160:163], v[206:209], v[110:113]
	v_mfma_f32_16x16x32_bf16 v[106:109], v[182:185], v[206:209], v[106:109]
	v_mfma_f32_16x16x32_bf16 v[94:97], v[160:163], v[214:217], v[94:97]
	v_mfma_f32_16x16x32_bf16 v[90:93], v[182:185], v[214:217], v[90:93]
	v_mfma_f32_16x16x32_bf16 v[78:81], v[160:163], v[222:225], v[78:81]
	v_mfma_f32_16x16x32_bf16 v[74:77], v[182:185], v[222:225], v[74:77]
	v_mfma_f32_16x16x32_bf16 v[70:73], v[160:163], v[230:233], v[70:73]
	v_mfma_f32_16x16x32_bf16 v[66:69], v[182:185], v[230:233], v[66:69]
	v_mfma_f32_16x16x32_bf16 v[110:113], v[178:181], v[210:213], v[110:113]
	v_mfma_f32_16x16x32_bf16 v[106:109], v[186:189], v[210:213], v[106:109]
	v_mfma_f32_16x16x32_bf16 v[94:97], v[178:181], v[218:221], v[94:97]
	v_mfma_f32_16x16x32_bf16 v[90:93], v[186:189], v[218:221], v[90:93]
	v_mfma_f32_16x16x32_bf16 v[78:81], v[178:181], v[226:229], v[78:81]
	v_mfma_f32_16x16x32_bf16 v[74:77], v[186:189], v[226:229], v[74:77]
	v_mfma_f32_16x16x32_bf16 v[70:73], v[178:181], v[234:237], v[70:73]
	v_mfma_f32_16x16x32_bf16 v[66:69], v[186:189], v[234:237], v[66:69]
	s_barrier
	s_setprio 0
	s_add_i32 s46, s62, s72
	v_lshl_add_u64 v[164:165], s[60:61], 0, v[166:167]
	s_mov_b32 m0, s46
	ds_read_b128 v[206:209], v142 offset:16384
	ds_read_b128 v[210:213], v142 offset:17408
	ds_read_b128 v[214:217], v142 offset:18432
	ds_read_b128 v[218:221], v142 offset:19456
	ds_read_b128 v[222:225], v142 offset:20480
	ds_read_b128 v[226:229], v142 offset:21504
	ds_read_b128 v[230:233], v142 offset:22528
	ds_read_b128 v[234:237], v142 offset:23552
	global_load_lds_dwordx4 v[164:165], off
	s_add_i32 m0, s46, 0x2000
	s_add_u32 s46, s60, 0x20000
	v_lshl_add_u64 v[242:243], s[60:61], 0, v[130:131]
	s_addc_u32 s47, s61, 0
	s_add_i32 s62, s63, s72
	global_load_lds_dwordx4 v[242:243], off
	v_lshl_add_u64 v[244:245], s[46:47], 0, v[166:167]
	s_mov_b32 m0, s62
	v_lshl_add_u64 v[246:247], s[68:69], 0, v[132:133]
	global_load_lds_dwordx4 v[244:245], off
	v_lshl_add_u64 v[244:245], s[46:47], 0, v[130:131]
	s_add_i32 m0, s62, 0x2000
	s_nop 0
	global_load_lds_dwordx4 v[244:245], off
	v_lshl_add_u64 v[244:245], s[68:69], 0, v[134:135]
	s_mov_b32 m0, s11
	s_nop 0
	global_load_lds_dwordx4 v[244:245], off
	s_mov_b32 m0, s74
	s_nop 0
	global_load_lds_dwordx4 v[246:247], off
	s_setprio 1
	s_waitcnt lgkmcnt(7)
	v_mfma_f32_16x16x32_bf16 v[62:65], v[144:147], v[206:209], v[62:65]
	v_mfma_f32_16x16x32_bf16 v[58:61], v[152:155], v[206:209], v[58:61]
	s_waitcnt lgkmcnt(5)
	v_mfma_f32_16x16x32_bf16 v[54:57], v[144:147], v[214:217], v[54:57]
	v_mfma_f32_16x16x32_bf16 v[50:53], v[152:155], v[214:217], v[50:53]
	s_waitcnt vmcnt(8)
	s_waitcnt lgkmcnt(0)
	s_barrier
	v_mfma_f32_16x16x32_bf16 v[38:41], v[144:147], v[222:225], v[38:41]
	v_mfma_f32_16x16x32_bf16 v[34:37], v[152:155], v[222:225], v[34:37]
	v_mfma_f32_16x16x32_bf16 v[22:25], v[144:147], v[230:233], v[22:25]
	v_mfma_f32_16x16x32_bf16 v[18:21], v[152:155], v[230:233], v[18:21]
	v_mfma_f32_16x16x32_bf16 v[62:65], v[148:151], v[210:213], v[62:65]
	v_mfma_f32_16x16x32_bf16 v[58:61], v[156:159], v[210:213], v[58:61]
	v_mfma_f32_16x16x32_bf16 v[54:57], v[148:151], v[218:221], v[54:57]
	v_mfma_f32_16x16x32_bf16 v[50:53], v[156:159], v[218:221], v[50:53]
	v_mfma_f32_16x16x32_bf16 v[38:41], v[148:151], v[226:229], v[38:41]
	v_mfma_f32_16x16x32_bf16 v[34:37], v[156:159], v[226:229], v[34:37]
	v_mfma_f32_16x16x32_bf16 v[22:25], v[148:151], v[234:237], v[22:25]
	v_mfma_f32_16x16x32_bf16 v[18:21], v[156:159], v[234:237], v[18:21]
	s_setprio 0
	s_setprio 1
	v_mfma_f32_16x16x32_bf16 v[46:49], v[160:163], v[206:209], v[46:49]
	v_mfma_f32_16x16x32_bf16 v[42:45], v[182:185], v[206:209], v[42:45]
	v_mfma_f32_16x16x32_bf16 v[30:33], v[160:163], v[214:217], v[30:33]
	v_mfma_f32_16x16x32_bf16 v[26:29], v[182:185], v[214:217], v[26:29]
	v_mfma_f32_16x16x32_bf16 v[14:17], v[160:163], v[222:225], v[14:17]
	v_mfma_f32_16x16x32_bf16 v[10:13], v[182:185], v[222:225], v[10:13]
	v_mfma_f32_16x16x32_bf16 v[6:9], v[160:163], v[230:233], v[6:9]
	v_mfma_f32_16x16x32_bf16 v[2:5], v[182:185], v[230:233], v[2:5]
	v_mfma_f32_16x16x32_bf16 v[46:49], v[178:181], v[210:213], v[46:49]
	v_mfma_f32_16x16x32_bf16 v[42:45], v[186:189], v[210:213], v[42:45]
	v_mfma_f32_16x16x32_bf16 v[30:33], v[178:181], v[218:221], v[30:33]
	v_mfma_f32_16x16x32_bf16 v[26:29], v[186:189], v[218:221], v[26:29]
	v_mfma_f32_16x16x32_bf16 v[14:17], v[178:181], v[226:229], v[14:17]
	v_mfma_f32_16x16x32_bf16 v[10:13], v[186:189], v[226:229], v[10:13]
	v_mfma_f32_16x16x32_bf16 v[6:9], v[178:181], v[234:237], v[6:9]
	v_mfma_f32_16x16x32_bf16 v[2:5], v[186:189], v[234:237], v[2:5]
	s_barrier
	s_setprio 0
	s_add_i32 s62, 0, 0x18000
	v_add_u32_e32 v143, s62, v140
	s_add_i32 s63, 0, 0x1c000
	ds_read_b128 v[144:147], v143
	ds_read_b128 v[148:151], v143 offset:1024
	ds_read_b128 v[152:155], v143 offset:2048
	ds_read_b128 v[156:159], v143 offset:3072
	v_add_u32_e32 v143, s63, v140
	ds_read_b128 v[160:163], v143
	ds_read_b128 v[178:181], v143 offset:1024
	ds_read_b128 v[182:185], v143 offset:2048
	ds_read_b128 v[186:189], v143 offset:3072
	s_add_u32 s46, s68, 0x20000
	s_addc_u32 s47, s69, 0
	s_mov_b32 m0, s75
	v_lshl_add_u64 v[248:249], s[46:47], 0, v[134:135]
	ds_read_b128 v[206:209], v142 offset:32768
	ds_read_b128 v[210:213], v142 offset:33792
	ds_read_b128 v[214:217], v142 offset:34816
	ds_read_b128 v[218:221], v142 offset:35840
	ds_read_b128 v[222:225], v142 offset:36864
	ds_read_b128 v[226:229], v142 offset:37888
	ds_read_b128 v[230:233], v142 offset:38912
	ds_read_b128 v[234:237], v142 offset:39936
	global_load_lds_dwordx4 v[248:249], off
	v_lshl_add_u64 v[248:249], s[46:47], 0, v[132:133]
	s_mov_b32 m0, s76
	s_nop 0
	global_load_lds_dwordx4 v[248:249], off
	s_setprio 1
	s_waitcnt lgkmcnt(7)
	v_mfma_f32_16x16x32_bf16 v[126:129], v[144:147], v[206:209], v[126:129]
	v_mfma_f32_16x16x32_bf16 v[122:125], v[152:155], v[206:209], v[122:125]
	s_waitcnt lgkmcnt(5)
	v_mfma_f32_16x16x32_bf16 v[118:121], v[144:147], v[214:217], v[118:121]
	v_mfma_f32_16x16x32_bf16 v[114:117], v[152:155], v[214:217], v[114:117]
	s_waitcnt vmcnt(8)
	s_waitcnt lgkmcnt(0)
	s_barrier
	v_mfma_f32_16x16x32_bf16 v[102:105], v[144:147], v[222:225], v[102:105]
	v_mfma_f32_16x16x32_bf16 v[98:101], v[152:155], v[222:225], v[98:101]
	v_mfma_f32_16x16x32_bf16 v[86:89], v[144:147], v[230:233], v[86:89]
	v_mfma_f32_16x16x32_bf16 v[82:85], v[152:155], v[230:233], v[82:85]
	v_mfma_f32_16x16x32_bf16 v[126:129], v[148:151], v[210:213], v[126:129]
	v_mfma_f32_16x16x32_bf16 v[122:125], v[156:159], v[210:213], v[122:125]
	v_mfma_f32_16x16x32_bf16 v[118:121], v[148:151], v[218:221], v[118:121]
	v_mfma_f32_16x16x32_bf16 v[114:117], v[156:159], v[218:221], v[114:117]
	v_mfma_f32_16x16x32_bf16 v[102:105], v[148:151], v[226:229], v[102:105]
	v_mfma_f32_16x16x32_bf16 v[98:101], v[156:159], v[226:229], v[98:101]
	v_mfma_f32_16x16x32_bf16 v[86:89], v[148:151], v[234:237], v[86:89]
	v_mfma_f32_16x16x32_bf16 v[82:85], v[156:159], v[234:237], v[82:85]
	s_setprio 0
	s_setprio 1
	v_mfma_f32_16x16x32_bf16 v[110:113], v[160:163], v[206:209], v[110:113]
	v_mfma_f32_16x16x32_bf16 v[106:109], v[182:185], v[206:209], v[106:109]
	v_mfma_f32_16x16x32_bf16 v[94:97], v[160:163], v[214:217], v[94:97]
	v_mfma_f32_16x16x32_bf16 v[90:93], v[182:185], v[214:217], v[90:93]
	v_mfma_f32_16x16x32_bf16 v[78:81], v[160:163], v[222:225], v[78:81]
	v_mfma_f32_16x16x32_bf16 v[74:77], v[182:185], v[222:225], v[74:77]
	v_mfma_f32_16x16x32_bf16 v[70:73], v[160:163], v[230:233], v[70:73]
	v_mfma_f32_16x16x32_bf16 v[66:69], v[182:185], v[230:233], v[66:69]
	v_mfma_f32_16x16x32_bf16 v[110:113], v[178:181], v[210:213], v[110:113]
	v_mfma_f32_16x16x32_bf16 v[106:109], v[186:189], v[210:213], v[106:109]
	v_mfma_f32_16x16x32_bf16 v[94:97], v[178:181], v[218:221], v[94:97]
	v_mfma_f32_16x16x32_bf16 v[90:93], v[186:189], v[218:221], v[90:93]
	v_mfma_f32_16x16x32_bf16 v[78:81], v[178:181], v[226:229], v[78:81]
	v_mfma_f32_16x16x32_bf16 v[74:77], v[186:189], v[226:229], v[74:77]
	v_mfma_f32_16x16x32_bf16 v[70:73], v[178:181], v[234:237], v[70:73]
	v_mfma_f32_16x16x32_bf16 v[66:69], v[186:189], v[234:237], v[66:69]
	s_barrier
	s_setprio 0
	s_add_i32 s46, s62, s72
	v_lshl_add_u64 v[164:165], v[164:165], 0, s[42:43]
	s_mov_b32 m0, s46
	ds_read_b128 v[206:209], v142 offset:49152
	ds_read_b128 v[210:213], v142 offset:50176
	ds_read_b128 v[214:217], v142 offset:51200
	ds_read_b128 v[218:221], v142 offset:52224
	ds_read_b128 v[222:225], v142 offset:53248
	ds_read_b128 v[226:229], v142 offset:54272
	ds_read_b128 v[230:233], v142 offset:55296
	ds_read_b128 v[234:237], v142 offset:56320
	global_load_lds_dwordx4 v[164:165], off
	s_add_i32 m0, s46, 0x2000
	s_add_u32 s46, s60, 0x20080
	v_lshl_add_u64 v[164:165], v[242:243], 0, s[42:43]
	s_addc_u32 s47, s61, 0
	s_add_i32 s60, s63, s72
	global_load_lds_dwordx4 v[164:165], off
	v_lshl_add_u64 v[164:165], s[46:47], 0, v[166:167]
	s_mov_b32 m0, s60
	s_nop 0
	global_load_lds_dwordx4 v[164:165], off
	v_lshl_add_u64 v[164:165], s[46:47], 0, v[130:131]
	s_add_i32 m0, s60, 0x2000
	s_nop 0
	global_load_lds_dwordx4 v[164:165], off
	v_lshl_add_u64 v[164:165], v[244:245], 0, s[42:43]
	s_mov_b32 m0, s77
	s_nop 0
	global_load_lds_dwordx4 v[164:165], off
	v_lshl_add_u64 v[164:165], v[246:247], 0, s[42:43]
	s_mov_b32 m0, s78
	s_nop 0
	global_load_lds_dwordx4 v[164:165], off
	s_setprio 1
	s_waitcnt lgkmcnt(7)
	v_mfma_f32_16x16x32_bf16 v[62:65], v[144:147], v[206:209], v[62:65]
	v_mfma_f32_16x16x32_bf16 v[58:61], v[152:155], v[206:209], v[58:61]
	s_waitcnt lgkmcnt(5)
	v_mfma_f32_16x16x32_bf16 v[54:57], v[144:147], v[214:217], v[54:57]
	v_mfma_f32_16x16x32_bf16 v[50:53], v[152:155], v[214:217], v[50:53]
	s_waitcnt vmcnt(8)
	s_waitcnt lgkmcnt(0)
	s_barrier
	v_mfma_f32_16x16x32_bf16 v[38:41], v[144:147], v[222:225], v[38:41]
	v_mfma_f32_16x16x32_bf16 v[34:37], v[152:155], v[222:225], v[34:37]
	v_mfma_f32_16x16x32_bf16 v[22:25], v[144:147], v[230:233], v[22:25]
	v_mfma_f32_16x16x32_bf16 v[18:21], v[152:155], v[230:233], v[18:21]
	v_mfma_f32_16x16x32_bf16 v[62:65], v[148:151], v[210:213], v[62:65]
	v_mfma_f32_16x16x32_bf16 v[58:61], v[156:159], v[210:213], v[58:61]
	v_mfma_f32_16x16x32_bf16 v[54:57], v[148:151], v[218:221], v[54:57]
	v_mfma_f32_16x16x32_bf16 v[50:53], v[156:159], v[218:221], v[50:53]
	v_mfma_f32_16x16x32_bf16 v[38:41], v[148:151], v[226:229], v[38:41]
	v_mfma_f32_16x16x32_bf16 v[34:37], v[156:159], v[226:229], v[34:37]
	v_mfma_f32_16x16x32_bf16 v[22:25], v[148:151], v[234:237], v[22:25]
	v_mfma_f32_16x16x32_bf16 v[18:21], v[156:159], v[234:237], v[18:21]
	s_setprio 0
	s_setprio 1
	v_mfma_f32_16x16x32_bf16 v[46:49], v[160:163], v[206:209], v[46:49]
	v_mfma_f32_16x16x32_bf16 v[42:45], v[182:185], v[206:209], v[42:45]
	v_mfma_f32_16x16x32_bf16 v[30:33], v[160:163], v[214:217], v[30:33]
	v_mfma_f32_16x16x32_bf16 v[26:29], v[182:185], v[214:217], v[26:29]
	v_mfma_f32_16x16x32_bf16 v[14:17], v[160:163], v[222:225], v[14:17]
	v_mfma_f32_16x16x32_bf16 v[10:13], v[182:185], v[222:225], v[10:13]
	v_mfma_f32_16x16x32_bf16 v[6:9], v[160:163], v[230:233], v[6:9]
	v_mfma_f32_16x16x32_bf16 v[2:5], v[182:185], v[230:233], v[2:5]
	v_mfma_f32_16x16x32_bf16 v[46:49], v[178:181], v[210:213], v[46:49]
	v_mfma_f32_16x16x32_bf16 v[42:45], v[186:189], v[210:213], v[42:45]
	v_mfma_f32_16x16x32_bf16 v[30:33], v[178:181], v[218:221], v[30:33]
	v_mfma_f32_16x16x32_bf16 v[26:29], v[186:189], v[218:221], v[26:29]
	v_mfma_f32_16x16x32_bf16 v[14:17], v[178:181], v[226:229], v[14:17]
	v_mfma_f32_16x16x32_bf16 v[10:13], v[186:189], v[226:229], v[10:13]
	v_mfma_f32_16x16x32_bf16 v[6:9], v[178:181], v[234:237], v[6:9]
	v_mfma_f32_16x16x32_bf16 v[2:5], v[186:189], v[234:237], v[2:5]
	s_barrier
	s_setprio 0
	s_add_i32 s84, s84, 2
	s_add_u32 s66, s66, 0x100
	s_addc_u32 s67, s67, 0
	s_add_u32 s82, s82, 0x100
	s_addc_u32 s83, s83, 0
	s_cmp_gt_u32 s84, 5
	s_cbranch_scc0 .LBB0_426
	s_and_b64 vcc, exec, s[12:13]
	s_cbranch_vccz .LBB0_429
	s_barrier

.LBB0_442:
	s_add_u32 s62, s18, s72
	s_addc_u32 s63, s19, 0
	s_add_u32 s73, s62, 0x100
	s_addc_u32 s74, s63, 0
	s_and_b64 s[46:47], s[60:61], exec
	s_cselect_b32 s75, s23, s74
	s_cselect_b32 s74, s92, s73
	s_add_u32 s46, s16, s72
	s_addc_u32 s47, s17, 0
	s_add_u32 s72, s46, 0x100
	s_addc_u32 s73, s47, 0
	s_add_i32 s48, 0, 0x10000
	s_and_b64 s[46:47], s[60:61], exec
	s_cselect_b32 s77, s21, s73
	s_cselect_b32 s76, s93, s72
	s_add_i32 s46, 0, 0x14000
	s_add_u32 s80, s62, 0x10080
	s_addc_u32 s81, s63, 0
	s_add_i32 s63, s48, s84
	s_add_i32 m0, s13, 0xc000
	s_add_i32 s49, s13, 0xe000
	s_add_i32 vcc_lo, s63, 0x2000
	v_add_u32_e32 v139, s48, v136
	s_add_u32 s78, s76, 0x10000
	ds_read_b128 v[140:143], v139
	ds_read_b128 v[144:147], v139 offset:1024
	ds_read_b128 v[148:151], v139 offset:2048
	ds_read_b128 v[152:155], v139 offset:3072
	v_add_u32_e32 v139, s46, v136
	s_addc_u32 s79, s77, 0
	s_add_i32 vcc_hi, s46, s84
	ds_read_b128 v[156:159], v139
	ds_read_b128 v[160:163], v139 offset:1024
	ds_read_b128 v[178:181], v139 offset:2048
	ds_read_b128 v[182:185], v139 offset:3072
	s_add_i32 s62, vcc_hi, 0x2000
	s_add_i32 s97, 0, 0x18000
	s_add_i32 s96, 0, 0x1c000
	s_add_u32 s72, s74, 0x10000
	s_addc_u32 s73, s75, 0
	s_add_i32 s95, s97, s84
	s_add_i32 s94, s95, 0x2000
	s_add_u32 s60, s76, 0x10080
	s_addc_u32 s61, s77, 0
	s_add_i32 s47, s96, s84
	s_add_i32 s46, s47, 0x2000
	v_lshl_add_u64 v[164:165], s[80:81], 0, v[134:135]
	ds_read_b128 v[186:189], v138
	ds_read_b128 v[206:209], v138 offset:1024
	ds_read_b128 v[210:213], v138 offset:2048
	ds_read_b128 v[214:217], v138 offset:3072
	ds_read_b128 v[218:221], v138 offset:4096
	ds_read_b128 v[222:225], v138 offset:5120
	ds_read_b128 v[226:229], v138 offset:6144
	ds_read_b128 v[230:233], v138 offset:7168
	global_load_lds_dwordx4 v[164:165], off
	v_lshl_add_u64 v[164:165], s[80:81], 0, v[132:133]
	s_mov_b32 m0, s49
	s_nop 0
	global_load_lds_dwordx4 v[164:165], off
	s_setprio 1
	s_waitcnt lgkmcnt(7)
	v_mfma_f32_16x16x32_bf16 v[126:129], v[140:143], v[186:189], v[126:129]
	v_mfma_f32_16x16x32_bf16 v[122:125], v[148:151], v[186:189], v[122:125]
	s_waitcnt lgkmcnt(5)
	v_mfma_f32_16x16x32_bf16 v[118:121], v[140:143], v[210:213], v[118:121]
	v_mfma_f32_16x16x32_bf16 v[114:117], v[148:151], v[210:213], v[114:117]
	s_waitcnt vmcnt(8)
	s_waitcnt lgkmcnt(0)
	s_barrier
	v_mfma_f32_16x16x32_bf16 v[102:105], v[140:143], v[218:221], v[102:105]
	v_mfma_f32_16x16x32_bf16 v[98:101], v[148:151], v[218:221], v[98:101]
	v_mfma_f32_16x16x32_bf16 v[86:89], v[140:143], v[226:229], v[86:89]
	v_mfma_f32_16x16x32_bf16 v[82:85], v[148:151], v[226:229], v[82:85]
	v_mfma_f32_16x16x32_bf16 v[126:129], v[144:147], v[206:209], v[126:129]
	v_mfma_f32_16x16x32_bf16 v[122:125], v[152:155], v[206:209], v[122:125]
	v_mfma_f32_16x16x32_bf16 v[118:121], v[144:147], v[214:217], v[118:121]
	v_mfma_f32_16x16x32_bf16 v[114:117], v[152:155], v[214:217], v[114:117]
	v_mfma_f32_16x16x32_bf16 v[102:105], v[144:147], v[222:225], v[102:105]
	v_mfma_f32_16x16x32_bf16 v[98:101], v[152:155], v[222:225], v[98:101]
	v_mfma_f32_16x16x32_bf16 v[86:89], v[144:147], v[230:233], v[86:89]
	v_mfma_f32_16x16x32_bf16 v[82:85], v[152:155], v[230:233], v[82:85]
	s_setprio 0
	s_setprio 1
	v_mfma_f32_16x16x32_bf16 v[110:113], v[156:159], v[186:189], v[110:113]
	v_mfma_f32_16x16x32_bf16 v[106:109], v[178:181], v[186:189], v[106:109]
	v_mfma_f32_16x16x32_bf16 v[94:97], v[156:159], v[210:213], v[94:97]
	v_mfma_f32_16x16x32_bf16 v[90:93], v[178:181], v[210:213], v[90:93]
	v_mfma_f32_16x16x32_bf16 v[78:81], v[156:159], v[218:221], v[78:81]
	v_mfma_f32_16x16x32_bf16 v[74:77], v[178:181], v[218:221], v[74:77]
	v_mfma_f32_16x16x32_bf16 v[70:73], v[156:159], v[226:229], v[70:73]
	v_mfma_f32_16x16x32_bf16 v[66:69], v[178:181], v[226:229], v[66:69]
	v_mfma_f32_16x16x32_bf16 v[110:113], v[160:163], v[206:209], v[110:113]
	v_mfma_f32_16x16x32_bf16 v[106:109], v[182:185], v[206:209], v[106:109]
	v_mfma_f32_16x16x32_bf16 v[94:97], v[160:163], v[214:217], v[94:97]
	v_mfma_f32_16x16x32_bf16 v[90:93], v[182:185], v[214:217], v[90:93]
	v_mfma_f32_16x16x32_bf16 v[78:81], v[160:163], v[222:225], v[78:81]
	v_mfma_f32_16x16x32_bf16 v[74:77], v[182:185], v[222:225], v[74:77]
	v_mfma_f32_16x16x32_bf16 v[70:73], v[160:163], v[230:233], v[70:73]
	v_mfma_f32_16x16x32_bf16 v[66:69], v[182:185], v[230:233], v[66:69]
	s_barrier
	s_setprio 0
	s_mov_b32 m0, s63
	v_lshl_add_u64 v[164:165], s[76:77], 0, v[166:167]
	ds_read_b128 v[186:189], v138 offset:16384
	ds_read_b128 v[206:209], v138 offset:17408
	ds_read_b128 v[210:213], v138 offset:18432
	ds_read_b128 v[214:217], v138 offset:19456
	ds_read_b128 v[218:221], v138 offset:20480
	ds_read_b128 v[222:225], v138 offset:21504
	ds_read_b128 v[226:229], v138 offset:22528
	ds_read_b128 v[230:233], v138 offset:23552
	global_load_lds_dwordx4 v[164:165], off
	v_lshl_add_u64 v[234:235], s[76:77], 0, v[130:131]
	s_mov_b32 m0, vcc_lo
	v_lshl_add_u64 v[236:237], s[78:79], 0, v[166:167]
	global_load_lds_dwordx4 v[234:235], off
	s_mov_b32 m0, vcc_hi
	v_lshl_add_u64 v[242:243], s[74:75], 0, v[132:133]
	global_load_lds_dwordx4 v[236:237], off
	v_lshl_add_u64 v[236:237], s[78:79], 0, v[130:131]
	s_mov_b32 m0, s62
	s_nop 0
	global_load_lds_dwordx4 v[236:237], off
	v_lshl_add_u64 v[236:237], s[74:75], 0, v[134:135]
	s_mov_b32 m0, s13
	s_nop 0
	global_load_lds_dwordx4 v[236:237], off
	s_mov_b32 m0, s86
	s_nop 0
	global_load_lds_dwordx4 v[242:243], off
	s_setprio 1
	s_waitcnt lgkmcnt(7)
	v_mfma_f32_16x16x32_bf16 v[62:65], v[140:143], v[186:189], v[62:65]
	v_mfma_f32_16x16x32_bf16 v[58:61], v[148:151], v[186:189], v[58:61]
	s_waitcnt lgkmcnt(5)
	v_mfma_f32_16x16x32_bf16 v[54:57], v[140:143], v[210:213], v[54:57]
	v_mfma_f32_16x16x32_bf16 v[50:53], v[148:151], v[210:213], v[50:53]
	s_waitcnt vmcnt(8)
	s_waitcnt lgkmcnt(0)
	s_barrier
	v_mfma_f32_16x16x32_bf16 v[38:41], v[140:143], v[218:221], v[38:41]
	v_mfma_f32_16x16x32_bf16 v[34:37], v[148:151], v[218:221], v[34:37]
	v_mfma_f32_16x16x32_bf16 v[22:25], v[140:143], v[226:229], v[22:25]
	v_mfma_f32_16x16x32_bf16 v[18:21], v[148:151], v[226:229], v[18:21]
	v_mfma_f32_16x16x32_bf16 v[62:65], v[144:147], v[206:209], v[62:65]
	v_mfma_f32_16x16x32_bf16 v[58:61], v[152:155], v[206:209], v[58:61]
	v_mfma_f32_16x16x32_bf16 v[54:57], v[144:147], v[214:217], v[54:57]
	v_mfma_f32_16x16x32_bf16 v[50:53], v[152:155], v[214:217], v[50:53]
	v_mfma_f32_16x16x32_bf16 v[38:41], v[144:147], v[222:225], v[38:41]
	v_mfma_f32_16x16x32_bf16 v[34:37], v[152:155], v[222:225], v[34:37]
	v_mfma_f32_16x16x32_bf16 v[22:25], v[144:147], v[230:233], v[22:25]
	v_mfma_f32_16x16x32_bf16 v[18:21], v[152:155], v[230:233], v[18:21]
	s_setprio 0
	s_setprio 1
	v_mfma_f32_16x16x32_bf16 v[46:49], v[156:159], v[186:189], v[46:49]
	v_mfma_f32_16x16x32_bf16 v[42:45], v[178:181], v[186:189], v[42:45]
	v_mfma_f32_16x16x32_bf16 v[30:33], v[156:159], v[210:213], v[30:33]
	v_mfma_f32_16x16x32_bf16 v[26:29], v[178:181], v[210:213], v[26:29]
	v_mfma_f32_16x16x32_bf16 v[14:17], v[156:159], v[218:221], v[14:17]
	v_mfma_f32_16x16x32_bf16 v[10:13], v[178:181], v[218:221], v[10:13]
	v_mfma_f32_16x16x32_bf16 v[6:9], v[156:159], v[226:229], v[6:9]
	v_mfma_f32_16x16x32_bf16 v[2:5], v[178:181], v[226:229], v[2:5]
	v_mfma_f32_16x16x32_bf16 v[46:49], v[160:163], v[206:209], v[46:49]
	v_mfma_f32_16x16x32_bf16 v[42:45], v[182:185], v[206:209], v[42:45]
	v_mfma_f32_16x16x32_bf16 v[30:33], v[160:163], v[214:217], v[30:33]
	v_mfma_f32_16x16x32_bf16 v[26:29], v[182:185], v[214:217], v[26:29]
	v_mfma_f32_16x16x32_bf16 v[14:17], v[160:163], v[222:225], v[14:17]
	v_mfma_f32_16x16x32_bf16 v[10:13], v[182:185], v[222:225], v[10:13]
	v_mfma_f32_16x16x32_bf16 v[6:9], v[160:163], v[230:233], v[6:9]
	v_mfma_f32_16x16x32_bf16 v[2:5], v[182:185], v[230:233], v[2:5]
	s_barrier
	s_setprio 0
	v_add_u32_e32 v139, s97, v136
	ds_read_b128 v[140:143], v139
	ds_read_b128 v[144:147], v139 offset:1024
	ds_read_b128 v[148:151], v139 offset:2048
	ds_read_b128 v[152:155], v139 offset:3072
	v_add_u32_e32 v139, s96, v136
	ds_read_b128 v[156:159], v139
	ds_read_b128 v[160:163], v139 offset:1024
	ds_read_b128 v[178:181], v139 offset:2048
	ds_read_b128 v[182:185], v139 offset:3072
	s_mov_b32 m0, s87
	v_lshl_add_u64 v[244:245], s[72:73], 0, v[134:135]
	ds_read_b128 v[186:189], v138 offset:32768
	ds_read_b128 v[206:209], v138 offset:33792
	ds_read_b128 v[210:213], v138 offset:34816
	ds_read_b128 v[214:217], v138 offset:35840
	ds_read_b128 v[218:221], v138 offset:36864
	ds_read_b128 v[222:225], v138 offset:37888
	ds_read_b128 v[226:229], v138 offset:38912
	ds_read_b128 v[230:233], v138 offset:39936
	global_load_lds_dwordx4 v[244:245], off
	v_lshl_add_u64 v[244:245], s[72:73], 0, v[132:133]
	s_mov_b32 m0, s88
	s_nop 0
	global_load_lds_dwordx4 v[244:245], off
	s_setprio 1
	s_waitcnt lgkmcnt(7)
	v_mfma_f32_16x16x32_bf16 v[126:129], v[140:143], v[186:189], v[126:129]
	v_mfma_f32_16x16x32_bf16 v[122:125], v[148:151], v[186:189], v[122:125]
	s_waitcnt lgkmcnt(5)
	v_mfma_f32_16x16x32_bf16 v[118:121], v[140:143], v[210:213], v[118:121]
	v_mfma_f32_16x16x32_bf16 v[114:117], v[148:151], v[210:213], v[114:117]
	s_waitcnt vmcnt(8)
	s_waitcnt lgkmcnt(0)
	s_barrier
	v_mfma_f32_16x16x32_bf16 v[102:105], v[140:143], v[218:221], v[102:105]
	v_mfma_f32_16x16x32_bf16 v[98:101], v[148:151], v[218:221], v[98:101]
	v_mfma_f32_16x16x32_bf16 v[86:89], v[140:143], v[226:229], v[86:89]
	v_mfma_f32_16x16x32_bf16 v[82:85], v[148:151], v[226:229], v[82:85]
	v_mfma_f32_16x16x32_bf16 v[126:129], v[144:147], v[206:209], v[126:129]
	v_mfma_f32_16x16x32_bf16 v[122:125], v[152:155], v[206:209], v[122:125]
	v_mfma_f32_16x16x32_bf16 v[118:121], v[144:147], v[214:217], v[118:121]
	v_mfma_f32_16x16x32_bf16 v[114:117], v[152:155], v[214:217], v[114:117]
	v_mfma_f32_16x16x32_bf16 v[102:105], v[144:147], v[222:225], v[102:105]
	v_mfma_f32_16x16x32_bf16 v[98:101], v[152:155], v[222:225], v[98:101]
	v_mfma_f32_16x16x32_bf16 v[86:89], v[144:147], v[230:233], v[86:89]
	v_mfma_f32_16x16x32_bf16 v[82:85], v[152:155], v[230:233], v[82:85]
	s_setprio 0
	s_setprio 1
	v_mfma_f32_16x16x32_bf16 v[110:113], v[156:159], v[186:189], v[110:113]
	v_mfma_f32_16x16x32_bf16 v[106:109], v[178:181], v[186:189], v[106:109]
	v_mfma_f32_16x16x32_bf16 v[94:97], v[156:159], v[210:213], v[94:97]
	v_mfma_f32_16x16x32_bf16 v[90:93], v[178:181], v[210:213], v[90:93]
	v_mfma_f32_16x16x32_bf16 v[78:81], v[156:159], v[218:221], v[78:81]
	v_mfma_f32_16x16x32_bf16 v[74:77], v[178:181], v[218:221], v[74:77]
	v_mfma_f32_16x16x32_bf16 v[70:73], v[156:159], v[226:229], v[70:73]
	v_mfma_f32_16x16x32_bf16 v[66:69], v[178:181], v[226:229], v[66:69]
	v_mfma_f32_16x16x32_bf16 v[110:113], v[160:163], v[206:209], v[110:113]
	v_mfma_f32_16x16x32_bf16 v[106:109], v[182:185], v[206:209], v[106:109]
	v_mfma_f32_16x16x32_bf16 v[94:97], v[160:163], v[214:217], v[94:97]
	v_mfma_f32_16x16x32_bf16 v[90:93], v[182:185], v[214:217], v[90:93]
	v_mfma_f32_16x16x32_bf16 v[78:81], v[160:163], v[222:225], v[78:81]
	v_mfma_f32_16x16x32_bf16 v[74:77], v[182:185], v[222:225], v[74:77]
	v_mfma_f32_16x16x32_bf16 v[70:73], v[160:163], v[230:233], v[70:73]
	v_mfma_f32_16x16x32_bf16 v[66:69], v[182:185], v[230:233], v[66:69]
	s_barrier
	s_setprio 0
	s_mov_b32 m0, s95
	v_lshl_add_u64 v[164:165], v[164:165], 0, s[42:43]
	ds_read_b128 v[186:189], v138 offset:49152
	ds_read_b128 v[206:209], v138 offset:50176
	ds_read_b128 v[210:213], v138 offset:51200
	ds_read_b128 v[214:217], v138 offset:52224
	ds_read_b128 v[218:221], v138 offset:53248
	ds_read_b128 v[222:225], v138 offset:54272
	ds_read_b128 v[226:229], v138 offset:55296
	ds_read_b128 v[230:233], v138 offset:56320
	global_load_lds_dwordx4 v[164:165], off
	v_lshl_add_u64 v[164:165], v[234:235], 0, s[42:43]
	s_mov_b32 m0, s94
	s_nop 0
	global_load_lds_dwordx4 v[164:165], off
	v_lshl_add_u64 v[164:165], s[60:61], 0, v[166:167]
	s_mov_b32 m0, s47
	s_nop 0
	global_load_lds_dwordx4 v[164:165], off
	v_lshl_add_u64 v[164:165], s[60:61], 0, v[130:131]
	s_mov_b32 m0, s46
	s_nop 0
	global_load_lds_dwordx4 v[164:165], off
	v_lshl_add_u64 v[164:165], v[236:237], 0, s[42:43]
	s_mov_b32 m0, s89
	s_nop 0
	global_load_lds_dwordx4 v[164:165], off
	v_lshl_add_u64 v[164:165], v[242:243], 0, s[42:43]
	s_mov_b32 m0, s90
	s_nop 0
	global_load_lds_dwordx4 v[164:165], off
	s_setprio 1
	s_waitcnt lgkmcnt(7)
	v_mfma_f32_16x16x32_bf16 v[62:65], v[140:143], v[186:189], v[62:65]
	v_mfma_f32_16x16x32_bf16 v[58:61], v[148:151], v[186:189], v[58:61]
	s_waitcnt lgkmcnt(5)
	v_mfma_f32_16x16x32_bf16 v[54:57], v[140:143], v[210:213], v[54:57]
	v_mfma_f32_16x16x32_bf16 v[50:53], v[148:151], v[210:213], v[50:53]
	s_waitcnt vmcnt(8)
	s_waitcnt lgkmcnt(0)
	s_barrier
	v_mfma_f32_16x16x32_bf16 v[38:41], v[140:143], v[218:221], v[38:41]
	v_mfma_f32_16x16x32_bf16 v[34:37], v[148:151], v[218:221], v[34:37]
	v_mfma_f32_16x16x32_bf16 v[22:25], v[140:143], v[226:229], v[22:25]
	v_mfma_f32_16x16x32_bf16 v[18:21], v[148:151], v[226:229], v[18:21]
	v_mfma_f32_16x16x32_bf16 v[62:65], v[144:147], v[206:209], v[62:65]
	v_mfma_f32_16x16x32_bf16 v[58:61], v[152:155], v[206:209], v[58:61]
	v_mfma_f32_16x16x32_bf16 v[54:57], v[144:147], v[214:217], v[54:57]
	v_mfma_f32_16x16x32_bf16 v[50:53], v[152:155], v[214:217], v[50:53]
	v_mfma_f32_16x16x32_bf16 v[38:41], v[144:147], v[222:225], v[38:41]
	v_mfma_f32_16x16x32_bf16 v[34:37], v[152:155], v[222:225], v[34:37]
	v_mfma_f32_16x16x32_bf16 v[22:25], v[144:147], v[230:233], v[22:25]
	v_mfma_f32_16x16x32_bf16 v[18:21], v[152:155], v[230:233], v[18:21]
	s_setprio 0
	s_setprio 1
	v_mfma_f32_16x16x32_bf16 v[46:49], v[156:159], v[186:189], v[46:49]
	v_mfma_f32_16x16x32_bf16 v[42:45], v[178:181], v[186:189], v[42:45]
	v_mfma_f32_16x16x32_bf16 v[30:33], v[156:159], v[210:213], v[30:33]
	v_mfma_f32_16x16x32_bf16 v[26:29], v[178:181], v[210:213], v[26:29]
	v_mfma_f32_16x16x32_bf16 v[14:17], v[156:159], v[218:221], v[14:17]
	v_mfma_f32_16x16x32_bf16 v[10:13], v[178:181], v[218:221], v[10:13]
	v_mfma_f32_16x16x32_bf16 v[6:9], v[156:159], v[226:229], v[6:9]
	v_mfma_f32_16x16x32_bf16 v[2:5], v[178:181], v[226:229], v[2:5]
	v_mfma_f32_16x16x32_bf16 v[46:49], v[160:163], v[206:209], v[46:49]
	v_mfma_f32_16x16x32_bf16 v[42:45], v[182:185], v[206:209], v[42:45]
	v_mfma_f32_16x16x32_bf16 v[30:33], v[160:163], v[214:217], v[30:33]
	v_mfma_f32_16x16x32_bf16 v[26:29], v[182:185], v[214:217], v[26:29]
	v_mfma_f32_16x16x32_bf16 v[14:17], v[160:163], v[222:225], v[14:17]
	v_mfma_f32_16x16x32_bf16 v[10:13], v[182:185], v[222:225], v[10:13]
	v_mfma_f32_16x16x32_bf16 v[6:9], v[160:163], v[230:233], v[6:9]
	v_mfma_f32_16x16x32_bf16 v[2:5], v[182:185], v[230:233], v[2:5]
	s_barrier
	s_setprio 0
	s_movk_i32 s72, 0x100
	s_andn2_b64 vcc, exec, s[70:71]
	s_mov_b64 s[60:61], -1
	s_mov_b64 s[70:71], 0
	s_cbranch_vccz .LBB0_442
	s_and_b64 vcc, exec, s[10:11]
	s_cbranch_vccz .LBB0_445
	s_barrier

.LBB0_795:
	s_add_u32 s46, s68, 0xfff80080
	s_addc_u32 s47, s69, -1
	s_add_i32 s48, 0, 0x10000
	s_cmp_eq_u32 s87, 28
	s_cselect_b32 s71, s19, s47
	s_cselect_b32 s70, s83, s46
	s_cselect_b32 s61, s17, s86
	s_cselect_b32 s60, s84, s85
	s_add_i32 s49, 0, 0x14000
	v_add_u32_e32 v156, s48, v1
	v_add_u32_e32 v164, s49, v1
	ds_read_b128 v[130:133], v156
	ds_read_b128 v[134:137], v156 offset:1024
	ds_read_b128 v[150:153], v156 offset:2048
	ds_read_b128 v[156:159], v156 offset:3072
	ds_read_b128 v[160:163], v164
	ds_read_b128 v[178:181], v164 offset:1024
	ds_read_b128 v[182:185], v164 offset:2048
	ds_read_b128 v[186:189], v164 offset:3072
	v_lshl_add_u64 v[164:165], s[68:69], 0, v[146:147]
	s_add_i32 m0, s67, 0xc000
	ds_read_b128 v[206:209], v155
	ds_read_b128 v[210:213], v155 offset:1024
	ds_read_b128 v[214:217], v155 offset:2048
	ds_read_b128 v[218:221], v155 offset:3072
	ds_read_b128 v[222:225], v155 offset:4096
	ds_read_b128 v[226:229], v155 offset:5120
	ds_read_b128 v[230:233], v155 offset:6144
	ds_read_b128 v[234:237], v155 offset:7168
	global_load_lds_dwordx4 v[164:165], off
	v_lshl_add_u64 v[164:165], s[68:69], 0, v[148:149]
	s_add_i32 m0, s67, 0xe000
	s_nop 0
	global_load_lds_dwordx4 v[164:165], off
	s_setprio 1
	s_waitcnt lgkmcnt(7)
	v_mfma_f32_16x16x32_bf16 v[126:129], v[130:133], v[206:209], v[126:129]
	v_mfma_f32_16x16x32_bf16 v[122:125], v[150:153], v[206:209], v[122:125]
	s_waitcnt lgkmcnt(5)
	v_mfma_f32_16x16x32_bf16 v[118:121], v[130:133], v[214:217], v[118:121]
	v_mfma_f32_16x16x32_bf16 v[114:117], v[150:153], v[214:217], v[114:117]
	s_waitcnt vmcnt(8)
	s_waitcnt lgkmcnt(0)
	s_barrier
	v_mfma_f32_16x16x32_bf16 v[110:113], v[130:133], v[222:225], v[110:113]
	v_mfma_f32_16x16x32_bf16 v[106:109], v[150:153], v[222:225], v[106:109]
	v_mfma_f32_16x16x32_bf16 v[102:105], v[130:133], v[230:233], v[102:105]
	v_mfma_f32_16x16x32_bf16 v[98:101], v[150:153], v[230:233], v[98:101]
	v_mfma_f32_16x16x32_bf16 v[126:129], v[134:137], v[210:213], v[126:129]
	v_mfma_f32_16x16x32_bf16 v[122:125], v[156:159], v[210:213], v[122:125]
	v_mfma_f32_16x16x32_bf16 v[118:121], v[134:137], v[218:221], v[118:121]
	v_mfma_f32_16x16x32_bf16 v[114:117], v[156:159], v[218:221], v[114:117]
	v_mfma_f32_16x16x32_bf16 v[110:113], v[134:137], v[226:229], v[110:113]
	v_mfma_f32_16x16x32_bf16 v[106:109], v[156:159], v[226:229], v[106:109]
	v_mfma_f32_16x16x32_bf16 v[102:105], v[134:137], v[234:237], v[102:105]
	v_mfma_f32_16x16x32_bf16 v[98:101], v[156:159], v[234:237], v[98:101]
	s_setprio 0
	s_setprio 1
	v_mfma_f32_16x16x32_bf16 v[66:69], v[160:163], v[206:209], v[66:69]
	v_mfma_f32_16x16x32_bf16 v[58:61], v[182:185], v[206:209], v[58:61]
	v_mfma_f32_16x16x32_bf16 v[54:57], v[160:163], v[214:217], v[54:57]
	v_mfma_f32_16x16x32_bf16 v[50:53], v[182:185], v[214:217], v[50:53]
	v_mfma_f32_16x16x32_bf16 v[46:49], v[160:163], v[222:225], v[46:49]
	v_mfma_f32_16x16x32_bf16 v[42:45], v[182:185], v[222:225], v[42:45]
	v_mfma_f32_16x16x32_bf16 v[38:41], v[160:163], v[230:233], v[38:41]
	v_mfma_f32_16x16x32_bf16 v[34:37], v[182:185], v[230:233], v[34:37]
	v_mfma_f32_16x16x32_bf16 v[66:69], v[178:181], v[210:213], v[66:69]
	v_mfma_f32_16x16x32_bf16 v[58:61], v[186:189], v[210:213], v[58:61]
	v_mfma_f32_16x16x32_bf16 v[54:57], v[178:181], v[218:221], v[54:57]
	v_mfma_f32_16x16x32_bf16 v[50:53], v[186:189], v[218:221], v[50:53]
	v_mfma_f32_16x16x32_bf16 v[46:49], v[178:181], v[226:229], v[46:49]
	v_mfma_f32_16x16x32_bf16 v[42:45], v[186:189], v[226:229], v[42:45]
	v_mfma_f32_16x16x32_bf16 v[38:41], v[178:181], v[234:237], v[38:41]
	v_mfma_f32_16x16x32_bf16 v[34:37], v[186:189], v[234:237], v[34:37]
	s_barrier
	s_setprio 0
	s_add_i32 s46, s48, s77
	v_lshl_add_u64 v[164:165], s[60:61], 0, v[166:167]
	s_mov_b32 m0, s46
	ds_read_b128 v[206:209], v155 offset:16384
	ds_read_b128 v[210:213], v155 offset:17408
	ds_read_b128 v[214:217], v155 offset:18432
	ds_read_b128 v[218:221], v155 offset:19456
	ds_read_b128 v[222:225], v155 offset:20480
	ds_read_b128 v[226:229], v155 offset:21504
	ds_read_b128 v[230:233], v155 offset:22528
	ds_read_b128 v[234:237], v155 offset:23552
	global_load_lds_dwordx4 v[164:165], off
	s_add_i32 m0, s46, 0x2000
	s_add_u32 s46, s60, 0x80000
	v_lshl_add_u64 v[242:243], s[60:61], 0, v[142:143]
	s_addc_u32 s47, s61, 0
	s_add_i32 s48, s49, s77
	global_load_lds_dwordx4 v[242:243], off
	v_lshl_add_u64 v[244:245], s[46:47], 0, v[166:167]
	s_mov_b32 m0, s48
	v_lshl_add_u64 v[246:247], s[70:71], 0, v[140:141]
	global_load_lds_dwordx4 v[244:245], off
	v_lshl_add_u64 v[244:245], s[46:47], 0, v[142:143]
	s_add_i32 m0, s48, 0x2000
	s_nop 0
	global_load_lds_dwordx4 v[244:245], off
	v_lshl_add_u64 v[244:245], s[70:71], 0, v[138:139]
	s_mov_b32 m0, s67
	s_nop 0
	global_load_lds_dwordx4 v[244:245], off
	s_mov_b32 m0, s78
	s_nop 0
	global_load_lds_dwordx4 v[246:247], off
	s_setprio 1
	s_waitcnt lgkmcnt(7)
	v_mfma_f32_16x16x32_bf16 v[94:97], v[130:133], v[206:209], v[94:97]
	v_mfma_f32_16x16x32_bf16 v[90:93], v[150:153], v[206:209], v[90:93]
	s_waitcnt lgkmcnt(5)
	v_mfma_f32_16x16x32_bf16 v[86:89], v[130:133], v[214:217], v[86:89]
	v_mfma_f32_16x16x32_bf16 v[82:85], v[150:153], v[214:217], v[82:85]
	s_waitcnt vmcnt(8)
	s_waitcnt lgkmcnt(0)
	s_barrier
	v_mfma_f32_16x16x32_bf16 v[78:81], v[130:133], v[222:225], v[78:81]
	v_mfma_f32_16x16x32_bf16 v[74:77], v[150:153], v[222:225], v[74:77]
	v_mfma_f32_16x16x32_bf16 v[70:73], v[130:133], v[230:233], v[70:73]
	v_mfma_f32_16x16x32_bf16 v[62:65], v[150:153], v[230:233], v[62:65]
	v_mfma_f32_16x16x32_bf16 v[94:97], v[134:137], v[210:213], v[94:97]
	v_mfma_f32_16x16x32_bf16 v[90:93], v[156:159], v[210:213], v[90:93]
	v_mfma_f32_16x16x32_bf16 v[86:89], v[134:137], v[218:221], v[86:89]
	v_mfma_f32_16x16x32_bf16 v[82:85], v[156:159], v[218:221], v[82:85]
	v_mfma_f32_16x16x32_bf16 v[78:81], v[134:137], v[226:229], v[78:81]
	v_mfma_f32_16x16x32_bf16 v[74:77], v[156:159], v[226:229], v[74:77]
	v_mfma_f32_16x16x32_bf16 v[70:73], v[134:137], v[234:237], v[70:73]
	v_mfma_f32_16x16x32_bf16 v[62:65], v[156:159], v[234:237], v[62:65]
	s_setprio 0
	s_setprio 1
	v_mfma_f32_16x16x32_bf16 v[30:33], v[160:163], v[206:209], v[30:33]
	v_mfma_f32_16x16x32_bf16 v[26:29], v[182:185], v[206:209], v[26:29]
	v_mfma_f32_16x16x32_bf16 v[22:25], v[160:163], v[214:217], v[22:25]
	v_mfma_f32_16x16x32_bf16 v[18:21], v[182:185], v[214:217], v[18:21]
	v_mfma_f32_16x16x32_bf16 v[14:17], v[160:163], v[222:225], v[14:17]
	v_mfma_f32_16x16x32_bf16 v[10:13], v[182:185], v[222:225], v[10:13]
	v_mfma_f32_16x16x32_bf16 v[6:9], v[160:163], v[230:233], v[6:9]
	v_mfma_f32_16x16x32_bf16 v[2:5], v[182:185], v[230:233], v[2:5]
	v_mfma_f32_16x16x32_bf16 v[30:33], v[178:181], v[210:213], v[30:33]
	v_mfma_f32_16x16x32_bf16 v[26:29], v[186:189], v[210:213], v[26:29]
	v_mfma_f32_16x16x32_bf16 v[22:25], v[178:181], v[218:221], v[22:25]
	v_mfma_f32_16x16x32_bf16 v[18:21], v[186:189], v[218:221], v[18:21]
	v_mfma_f32_16x16x32_bf16 v[14:17], v[178:181], v[226:229], v[14:17]
	v_mfma_f32_16x16x32_bf16 v[10:13], v[186:189], v[226:229], v[10:13]
	v_mfma_f32_16x16x32_bf16 v[6:9], v[178:181], v[234:237], v[6:9]
	v_mfma_f32_16x16x32_bf16 v[2:5], v[186:189], v[234:237], v[2:5]
	s_barrier
	s_setprio 0
	s_add_i32 s48, 0, 0x18000
	s_add_i32 s49, 0, 0x1c000
	v_add_u32_e32 v156, s48, v1
	v_add_u32_e32 v186, s49, v1
	ds_read_b128 v[130:133], v156
	ds_read_b128 v[134:137], v156 offset:1024
	ds_read_b128 v[150:153], v156 offset:2048
	ds_read_b128 v[156:159], v156 offset:3072
	ds_read_b128 v[160:163], v186
	ds_read_b128 v[178:181], v186 offset:1024
	ds_read_b128 v[182:185], v186 offset:2048
	ds_read_b128 v[186:189], v186 offset:3072
	s_add_u32 s46, s70, 0x80000
	s_addc_u32 s47, s71, 0
	s_mov_b32 m0, s79
	v_lshl_add_u64 v[248:249], s[46:47], 0, v[138:139]
	ds_read_b128 v[206:209], v155 offset:32768
	ds_read_b128 v[210:213], v155 offset:33792
	ds_read_b128 v[214:217], v155 offset:34816
	ds_read_b128 v[218:221], v155 offset:35840
	ds_read_b128 v[222:225], v155 offset:36864
	ds_read_b128 v[226:229], v155 offset:37888
	ds_read_b128 v[230:233], v155 offset:38912
	ds_read_b128 v[234:237], v155 offset:39936
	global_load_lds_dwordx4 v[248:249], off
	v_lshl_add_u64 v[248:249], s[46:47], 0, v[140:141]
	s_mov_b32 m0, s80
	s_nop 0
	global_load_lds_dwordx4 v[248:249], off
	s_setprio 1
	s_waitcnt lgkmcnt(7)
	v_mfma_f32_16x16x32_bf16 v[126:129], v[130:133], v[206:209], v[126:129]
	v_mfma_f32_16x16x32_bf16 v[122:125], v[150:153], v[206:209], v[122:125]
	s_waitcnt lgkmcnt(5)
	v_mfma_f32_16x16x32_bf16 v[118:121], v[130:133], v[214:217], v[118:121]
	v_mfma_f32_16x16x32_bf16 v[114:117], v[150:153], v[214:217], v[114:117]
	s_waitcnt vmcnt(8)
	s_waitcnt lgkmcnt(0)
	s_barrier
	v_mfma_f32_16x16x32_bf16 v[110:113], v[130:133], v[222:225], v[110:113]
	v_mfma_f32_16x16x32_bf16 v[106:109], v[150:153], v[222:225], v[106:109]
	v_mfma_f32_16x16x32_bf16 v[102:105], v[130:133], v[230:233], v[102:105]
	v_mfma_f32_16x16x32_bf16 v[98:101], v[150:153], v[230:233], v[98:101]
	v_mfma_f32_16x16x32_bf16 v[126:129], v[134:137], v[210:213], v[126:129]
	v_mfma_f32_16x16x32_bf16 v[122:125], v[156:159], v[210:213], v[122:125]
	v_mfma_f32_16x16x32_bf16 v[118:121], v[134:137], v[218:221], v[118:121]
	v_mfma_f32_16x16x32_bf16 v[114:117], v[156:159], v[218:221], v[114:117]
	v_mfma_f32_16x16x32_bf16 v[110:113], v[134:137], v[226:229], v[110:113]
	v_mfma_f32_16x16x32_bf16 v[106:109], v[156:159], v[226:229], v[106:109]
	v_mfma_f32_16x16x32_bf16 v[102:105], v[134:137], v[234:237], v[102:105]
	v_mfma_f32_16x16x32_bf16 v[98:101], v[156:159], v[234:237], v[98:101]
	s_setprio 0
	s_setprio 1
	v_mfma_f32_16x16x32_bf16 v[66:69], v[160:163], v[206:209], v[66:69]
	v_mfma_f32_16x16x32_bf16 v[58:61], v[182:185], v[206:209], v[58:61]
	v_mfma_f32_16x16x32_bf16 v[54:57], v[160:163], v[214:217], v[54:57]
	v_mfma_f32_16x16x32_bf16 v[50:53], v[182:185], v[214:217], v[50:53]
	v_mfma_f32_16x16x32_bf16 v[46:49], v[160:163], v[222:225], v[46:49]
	v_mfma_f32_16x16x32_bf16 v[42:45], v[182:185], v[222:225], v[42:45]
	v_mfma_f32_16x16x32_bf16 v[38:41], v[160:163], v[230:233], v[38:41]
	v_mfma_f32_16x16x32_bf16 v[34:37], v[182:185], v[230:233], v[34:37]
	v_mfma_f32_16x16x32_bf16 v[66:69], v[178:181], v[210:213], v[66:69]
	v_mfma_f32_16x16x32_bf16 v[58:61], v[186:189], v[210:213], v[58:61]
	v_mfma_f32_16x16x32_bf16 v[54:57], v[178:181], v[218:221], v[54:57]
	v_mfma_f32_16x16x32_bf16 v[50:53], v[186:189], v[218:221], v[50:53]
	v_mfma_f32_16x16x32_bf16 v[46:49], v[178:181], v[226:229], v[46:49]
	v_mfma_f32_16x16x32_bf16 v[42:45], v[186:189], v[226:229], v[42:45]
	v_mfma_f32_16x16x32_bf16 v[38:41], v[178:181], v[234:237], v[38:41]
	v_mfma_f32_16x16x32_bf16 v[34:37], v[186:189], v[234:237], v[34:37]
	s_barrier
	s_setprio 0
	s_add_i32 s46, s48, s77
	v_lshl_add_u64 v[164:165], v[164:165], 0, s[42:43]
	s_mov_b32 m0, s46
	ds_read_b128 v[206:209], v155 offset:49152
	ds_read_b128 v[210:213], v155 offset:50176
	ds_read_b128 v[214:217], v155 offset:51200
	ds_read_b128 v[218:221], v155 offset:52224
	ds_read_b128 v[222:225], v155 offset:53248
	ds_read_b128 v[226:229], v155 offset:54272
	ds_read_b128 v[230:233], v155 offset:55296
	ds_read_b128 v[234:237], v155 offset:56320
	global_load_lds_dwordx4 v[164:165], off
	s_add_i32 m0, s46, 0x2000
	s_add_u32 s46, s60, 0x80080
	v_lshl_add_u64 v[164:165], v[242:243], 0, s[42:43]
	s_addc_u32 s47, s61, 0
	s_add_i32 s48, s49, s77
	global_load_lds_dwordx4 v[164:165], off
	v_lshl_add_u64 v[164:165], s[46:47], 0, v[166:167]
	s_mov_b32 m0, s48
	s_nop 0
	global_load_lds_dwordx4 v[164:165], off
	v_lshl_add_u64 v[164:165], s[46:47], 0, v[142:143]
	s_add_i32 m0, s48, 0x2000
	s_nop 0
	global_load_lds_dwordx4 v[164:165], off
	v_lshl_add_u64 v[164:165], v[244:245], 0, s[42:43]
	s_mov_b32 m0, s26
	s_nop 0
	global_load_lds_dwordx4 v[164:165], off
	v_lshl_add_u64 v[164:165], v[246:247], 0, s[42:43]
	s_mov_b32 m0, s81
	s_nop 0
	global_load_lds_dwordx4 v[164:165], off
	s_setprio 1
	s_waitcnt lgkmcnt(7)
	v_mfma_f32_16x16x32_bf16 v[94:97], v[130:133], v[206:209], v[94:97]
	v_mfma_f32_16x16x32_bf16 v[90:93], v[150:153], v[206:209], v[90:93]
	s_waitcnt lgkmcnt(5)
	v_mfma_f32_16x16x32_bf16 v[86:89], v[130:133], v[214:217], v[86:89]
	v_mfma_f32_16x16x32_bf16 v[82:85], v[150:153], v[214:217], v[82:85]
	s_waitcnt vmcnt(8)
	s_waitcnt lgkmcnt(0)
	s_barrier
	v_mfma_f32_16x16x32_bf16 v[78:81], v[130:133], v[222:225], v[78:81]
	v_mfma_f32_16x16x32_bf16 v[74:77], v[150:153], v[222:225], v[74:77]
	v_mfma_f32_16x16x32_bf16 v[70:73], v[130:133], v[230:233], v[70:73]
	v_mfma_f32_16x16x32_bf16 v[62:65], v[150:153], v[230:233], v[62:65]
	v_mfma_f32_16x16x32_bf16 v[94:97], v[134:137], v[210:213], v[94:97]
	v_mfma_f32_16x16x32_bf16 v[90:93], v[156:159], v[210:213], v[90:93]
	v_mfma_f32_16x16x32_bf16 v[86:89], v[134:137], v[218:221], v[86:89]
	v_mfma_f32_16x16x32_bf16 v[82:85], v[156:159], v[218:221], v[82:85]
	v_mfma_f32_16x16x32_bf16 v[78:81], v[134:137], v[226:229], v[78:81]
	v_mfma_f32_16x16x32_bf16 v[74:77], v[156:159], v[226:229], v[74:77]
	v_mfma_f32_16x16x32_bf16 v[70:73], v[134:137], v[234:237], v[70:73]
	v_mfma_f32_16x16x32_bf16 v[62:65], v[156:159], v[234:237], v[62:65]
	s_setprio 0
	s_setprio 1
	v_mfma_f32_16x16x32_bf16 v[30:33], v[160:163], v[206:209], v[30:33]
	v_mfma_f32_16x16x32_bf16 v[26:29], v[182:185], v[206:209], v[26:29]
	v_mfma_f32_16x16x32_bf16 v[22:25], v[160:163], v[214:217], v[22:25]
	v_mfma_f32_16x16x32_bf16 v[18:21], v[182:185], v[214:217], v[18:21]
	v_mfma_f32_16x16x32_bf16 v[14:17], v[160:163], v[222:225], v[14:17]
	v_mfma_f32_16x16x32_bf16 v[10:13], v[182:185], v[222:225], v[10:13]
	v_mfma_f32_16x16x32_bf16 v[6:9], v[160:163], v[230:233], v[6:9]
	v_mfma_f32_16x16x32_bf16 v[2:5], v[182:185], v[230:233], v[2:5]
	v_mfma_f32_16x16x32_bf16 v[30:33], v[178:181], v[210:213], v[30:33]
	v_mfma_f32_16x16x32_bf16 v[26:29], v[186:189], v[210:213], v[26:29]
	v_mfma_f32_16x16x32_bf16 v[22:25], v[178:181], v[218:221], v[22:25]
	v_mfma_f32_16x16x32_bf16 v[18:21], v[186:189], v[218:221], v[18:21]
	v_mfma_f32_16x16x32_bf16 v[14:17], v[178:181], v[226:229], v[14:17]
	v_mfma_f32_16x16x32_bf16 v[10:13], v[186:189], v[226:229], v[10:13]
	v_mfma_f32_16x16x32_bf16 v[6:9], v[178:181], v[234:237], v[6:9]
	v_mfma_f32_16x16x32_bf16 v[2:5], v[186:189], v[234:237], v[2:5]
	s_barrier
	s_setprio 0
	s_add_i32 s87, s87, 2
	s_add_u32 s68, s68, 0x100
	s_addc_u32 s69, s69, 0
	s_add_u32 s85, s85, 0x100
	s_addc_u32 s86, s86, 0
	s_cmp_gt_u32 s87, 29
	s_cbranch_scc0 .LBB0_795
	s_and_b64 vcc, exec, s[12:13]
	s_cbranch_vccz .LBB0_798
	s_barrier

.LBB0_819:
	s_add_i32 s93, s60, 2
	s_add_u32 s46, s72, 0x80
	s_addc_u32 s47, s73, 0
	s_add_i32 s48, 0, 0x10000
	s_cmp_eq_u32 s87, s60
	s_cselect_b32 s61, s23, s47
	s_cselect_b32 s60, s64, s46
	s_cselect_b32 s47, s21, s92
	s_cselect_b32 s46, s90, s91
	s_add_i32 s49, 0, 0x14000
	v_add_u32_e32 v142, s48, v205
	v_add_u32_e32 v182, s49, v205
	ds_read_b128 v[130:133], v142
	ds_read_b128 v[134:137], v142 offset:1024
	ds_read_b128 v[138:141], v142 offset:2048
	ds_read_b128 v[142:145], v142 offset:3072
	ds_read_b128 v[146:149], v182
	ds_read_b128 v[150:153], v182 offset:1024
	ds_read_b128 v[178:181], v182 offset:2048
	ds_read_b128 v[182:185], v182 offset:3072
	v_lshl_add_u64 v[236:237], s[72:73], 0, v[162:163]
	s_add_i32 m0, s71, 0xc000
	ds_read_b128 v[186:189], v207
	ds_read_b128 v[208:211], v207 offset:1024
	ds_read_b128 v[212:215], v207 offset:2048
	ds_read_b128 v[216:219], v207 offset:3072
	ds_read_b128 v[220:223], v207 offset:4096
	ds_read_b128 v[224:227], v207 offset:5120
	ds_read_b128 v[228:231], v207 offset:6144
	ds_read_b128 v[232:235], v207 offset:7168
	global_load_lds_dwordx4 v[236:237], off
	v_lshl_add_u64 v[236:237], s[72:73], 0, v[164:165]
	s_add_i32 m0, s71, 0xe000
	s_nop 0
	global_load_lds_dwordx4 v[236:237], off
	s_setprio 1
	s_waitcnt lgkmcnt(7)
	v_mfma_f32_16x16x32_bf16 v[126:129], v[130:133], v[186:189], v[126:129]
	v_mfma_f32_16x16x32_bf16 v[122:125], v[138:141], v[186:189], v[122:125]
	s_waitcnt lgkmcnt(5)
	v_mfma_f32_16x16x32_bf16 v[118:121], v[130:133], v[212:215], v[118:121]
	v_mfma_f32_16x16x32_bf16 v[114:117], v[138:141], v[212:215], v[114:117]
	s_waitcnt vmcnt(8)
	s_waitcnt lgkmcnt(0)
	s_barrier
	v_mfma_f32_16x16x32_bf16 v[110:113], v[130:133], v[220:223], v[110:113]
	v_mfma_f32_16x16x32_bf16 v[106:109], v[138:141], v[220:223], v[106:109]
	v_mfma_f32_16x16x32_bf16 v[102:105], v[130:133], v[228:231], v[102:105]
	v_mfma_f32_16x16x32_bf16 v[98:101], v[138:141], v[228:231], v[98:101]
	v_mfma_f32_16x16x32_bf16 v[126:129], v[134:137], v[208:211], v[126:129]
	v_mfma_f32_16x16x32_bf16 v[122:125], v[142:145], v[208:211], v[122:125]
	v_mfma_f32_16x16x32_bf16 v[118:121], v[134:137], v[216:219], v[118:121]
	v_mfma_f32_16x16x32_bf16 v[114:117], v[142:145], v[216:219], v[114:117]
	v_mfma_f32_16x16x32_bf16 v[110:113], v[134:137], v[224:227], v[110:113]
	v_mfma_f32_16x16x32_bf16 v[106:109], v[142:145], v[224:227], v[106:109]
	v_mfma_f32_16x16x32_bf16 v[102:105], v[134:137], v[232:235], v[102:105]
	v_mfma_f32_16x16x32_bf16 v[98:101], v[142:145], v[232:235], v[98:101]
	s_setprio 0
	s_setprio 1
	v_mfma_f32_16x16x32_bf16 v[94:97], v[146:149], v[186:189], v[94:97]
	v_mfma_f32_16x16x32_bf16 v[90:93], v[178:181], v[186:189], v[90:93]
	v_mfma_f32_16x16x32_bf16 v[86:89], v[146:149], v[212:215], v[86:89]
	v_mfma_f32_16x16x32_bf16 v[82:85], v[178:181], v[212:215], v[82:85]
	v_mfma_f32_16x16x32_bf16 v[78:81], v[146:149], v[220:223], v[78:81]
	v_mfma_f32_16x16x32_bf16 v[74:77], v[178:181], v[220:223], v[74:77]
	v_mfma_f32_16x16x32_bf16 v[70:73], v[146:149], v[228:231], v[70:73]
	v_mfma_f32_16x16x32_bf16 v[66:69], v[178:181], v[228:231], v[66:69]
	v_mfma_f32_16x16x32_bf16 v[94:97], v[150:153], v[208:211], v[94:97]
	v_mfma_f32_16x16x32_bf16 v[90:93], v[182:185], v[208:211], v[90:93]
	v_mfma_f32_16x16x32_bf16 v[86:89], v[150:153], v[216:219], v[86:89]
	v_mfma_f32_16x16x32_bf16 v[82:85], v[182:185], v[216:219], v[82:85]
	v_mfma_f32_16x16x32_bf16 v[78:81], v[150:153], v[224:227], v[78:81]
	v_mfma_f32_16x16x32_bf16 v[74:77], v[182:185], v[224:227], v[74:77]
	v_mfma_f32_16x16x32_bf16 v[70:73], v[150:153], v[232:235], v[70:73]
	v_mfma_f32_16x16x32_bf16 v[66:69], v[182:185], v[232:235], v[66:69]
	s_barrier
	s_setprio 0
	s_add_i32 s48, s48, s80
	v_lshl_add_u64 v[236:237], s[46:47], 0, v[166:167]
	s_mov_b32 m0, s48
	ds_read_b128 v[186:189], v207 offset:16384
	ds_read_b128 v[208:211], v207 offset:17408
	ds_read_b128 v[212:215], v207 offset:18432
	ds_read_b128 v[216:219], v207 offset:19456
	ds_read_b128 v[220:223], v207 offset:20480
	ds_read_b128 v[224:227], v207 offset:21504
	ds_read_b128 v[228:231], v207 offset:22528
	ds_read_b128 v[232:235], v207 offset:23552
	global_load_lds_dwordx4 v[236:237], off
	s_add_i32 m0, s48, 0x2000
	v_lshl_add_u64 v[242:243], s[46:47], 0, v[158:159]
	s_add_u32 s46, s46, s26
	s_addc_u32 s47, s47, 0
	s_add_i32 s48, s49, s80
	global_load_lds_dwordx4 v[242:243], off
	v_lshl_add_u64 v[244:245], s[46:47], 0, v[166:167]
	s_mov_b32 m0, s48
	v_lshl_add_u64 v[246:247], s[46:47], 0, v[158:159]
	global_load_lds_dwordx4 v[244:245], off
	s_add_i32 m0, s48, 0x2000
	v_lshl_add_u64 v[248:249], s[60:61], 0, v[154:155]
	global_load_lds_dwordx4 v[246:247], off
	s_mov_b32 m0, s71
	v_lshl_add_u64 v[250:251], s[60:61], 0, v[156:157]
	global_load_lds_dwordx4 v[248:249], off
	s_mov_b32 m0, s81
	s_nop 0
	global_load_lds_dwordx4 v[250:251], off
	s_setprio 1
	s_waitcnt lgkmcnt(7)
	v_mfma_f32_16x16x32_bf16 v[62:65], v[130:133], v[186:189], v[62:65]
	v_mfma_f32_16x16x32_bf16 v[58:61], v[138:141], v[186:189], v[58:61]
	s_waitcnt lgkmcnt(5)
	v_mfma_f32_16x16x32_bf16 v[54:57], v[130:133], v[212:215], v[54:57]
	v_mfma_f32_16x16x32_bf16 v[50:53], v[138:141], v[212:215], v[50:53]
	s_waitcnt vmcnt(8)
	s_waitcnt lgkmcnt(0)
	s_barrier
	v_mfma_f32_16x16x32_bf16 v[46:49], v[130:133], v[220:223], v[46:49]
	v_mfma_f32_16x16x32_bf16 v[42:45], v[138:141], v[220:223], v[42:45]
	v_mfma_f32_16x16x32_bf16 v[38:41], v[130:133], v[228:231], v[38:41]
	v_mfma_f32_16x16x32_bf16 v[34:37], v[138:141], v[228:231], v[34:37]
	v_mfma_f32_16x16x32_bf16 v[62:65], v[134:137], v[208:211], v[62:65]
	v_mfma_f32_16x16x32_bf16 v[58:61], v[142:145], v[208:211], v[58:61]
	v_mfma_f32_16x16x32_bf16 v[54:57], v[134:137], v[216:219], v[54:57]
	v_mfma_f32_16x16x32_bf16 v[50:53], v[142:145], v[216:219], v[50:53]
	v_mfma_f32_16x16x32_bf16 v[46:49], v[134:137], v[224:227], v[46:49]
	v_mfma_f32_16x16x32_bf16 v[42:45], v[142:145], v[224:227], v[42:45]
	v_mfma_f32_16x16x32_bf16 v[38:41], v[134:137], v[232:235], v[38:41]
	v_mfma_f32_16x16x32_bf16 v[34:37], v[142:145], v[232:235], v[34:37]
	s_setprio 0
	s_setprio 1
	v_mfma_f32_16x16x32_bf16 v[30:33], v[146:149], v[186:189], v[30:33]
	v_mfma_f32_16x16x32_bf16 v[26:29], v[178:181], v[186:189], v[26:29]
	v_mfma_f32_16x16x32_bf16 v[22:25], v[146:149], v[212:215], v[22:25]
	v_mfma_f32_16x16x32_bf16 v[18:21], v[178:181], v[212:215], v[18:21]
	v_mfma_f32_16x16x32_bf16 v[14:17], v[146:149], v[220:223], v[14:17]
	v_mfma_f32_16x16x32_bf16 v[10:13], v[178:181], v[220:223], v[10:13]
	v_mfma_f32_16x16x32_bf16 v[6:9], v[146:149], v[228:231], v[6:9]
	v_mfma_f32_16x16x32_bf16 v[2:5], v[178:181], v[228:231], v[2:5]
	v_mfma_f32_16x16x32_bf16 v[30:33], v[150:153], v[208:211], v[30:33]
	v_mfma_f32_16x16x32_bf16 v[26:29], v[182:185], v[208:211], v[26:29]
	v_mfma_f32_16x16x32_bf16 v[22:25], v[150:153], v[216:219], v[22:25]
	v_mfma_f32_16x16x32_bf16 v[18:21], v[182:185], v[216:219], v[18:21]
	v_mfma_f32_16x16x32_bf16 v[14:17], v[150:153], v[224:227], v[14:17]
	v_mfma_f32_16x16x32_bf16 v[10:13], v[182:185], v[224:227], v[10:13]
	v_mfma_f32_16x16x32_bf16 v[6:9], v[150:153], v[232:235], v[6:9]
	v_mfma_f32_16x16x32_bf16 v[2:5], v[182:185], v[232:235], v[2:5]
	s_barrier
	s_setprio 0
	s_add_i32 s48, 0, 0x18000
	s_add_i32 s49, 0, 0x1c000
	v_add_u32_e32 v142, s48, v205
	v_add_u32_e32 v182, s49, v205
	ds_read_b128 v[130:133], v142
	ds_read_b128 v[134:137], v142 offset:1024
	ds_read_b128 v[138:141], v142 offset:2048
	ds_read_b128 v[142:145], v142 offset:3072
	ds_read_b128 v[146:149], v182
	ds_read_b128 v[150:153], v182 offset:1024
	ds_read_b128 v[178:181], v182 offset:2048
	ds_read_b128 v[182:185], v182 offset:3072
	s_add_u32 s46, s60, s26
	s_addc_u32 s47, s61, 0
	s_mov_b32 m0, s82
	v_lshl_add_u64 v[252:253], s[46:47], 0, v[154:155]
	ds_read_b128 v[186:189], v207 offset:32768
	ds_read_b128 v[208:211], v207 offset:33792
	ds_read_b128 v[212:215], v207 offset:34816
	ds_read_b128 v[216:219], v207 offset:35840
	ds_read_b128 v[220:223], v207 offset:36864
	ds_read_b128 v[224:227], v207 offset:37888
	ds_read_b128 v[228:231], v207 offset:38912
	ds_read_b128 v[232:235], v207 offset:39936
	global_load_lds_dwordx4 v[252:253], off
	v_lshl_add_u64 v[252:253], s[46:47], 0, v[156:157]
	s_mov_b32 m0, s83
	s_nop 0
	global_load_lds_dwordx4 v[252:253], off
	s_setprio 1
	s_waitcnt lgkmcnt(7)
	v_mfma_f32_16x16x32_bf16 v[126:129], v[130:133], v[186:189], v[126:129]
	v_mfma_f32_16x16x32_bf16 v[122:125], v[138:141], v[186:189], v[122:125]
	s_waitcnt lgkmcnt(5)
	v_mfma_f32_16x16x32_bf16 v[118:121], v[130:133], v[212:215], v[118:121]
	v_mfma_f32_16x16x32_bf16 v[114:117], v[138:141], v[212:215], v[114:117]
	s_waitcnt vmcnt(8)
	s_waitcnt lgkmcnt(0)
	s_barrier
	v_mfma_f32_16x16x32_bf16 v[110:113], v[130:133], v[220:223], v[110:113]
	v_mfma_f32_16x16x32_bf16 v[106:109], v[138:141], v[220:223], v[106:109]
	v_mfma_f32_16x16x32_bf16 v[102:105], v[130:133], v[228:231], v[102:105]
	v_mfma_f32_16x16x32_bf16 v[98:101], v[138:141], v[228:231], v[98:101]
	v_mfma_f32_16x16x32_bf16 v[126:129], v[134:137], v[208:211], v[126:129]
	v_mfma_f32_16x16x32_bf16 v[122:125], v[142:145], v[208:211], v[122:125]
	v_mfma_f32_16x16x32_bf16 v[118:121], v[134:137], v[216:219], v[118:121]
	v_mfma_f32_16x16x32_bf16 v[114:117], v[142:145], v[216:219], v[114:117]
	v_mfma_f32_16x16x32_bf16 v[110:113], v[134:137], v[224:227], v[110:113]
	v_mfma_f32_16x16x32_bf16 v[106:109], v[142:145], v[224:227], v[106:109]
	v_mfma_f32_16x16x32_bf16 v[102:105], v[134:137], v[232:235], v[102:105]
	v_mfma_f32_16x16x32_bf16 v[98:101], v[142:145], v[232:235], v[98:101]
	s_setprio 0
	s_setprio 1
	v_mfma_f32_16x16x32_bf16 v[94:97], v[146:149], v[186:189], v[94:97]
	v_mfma_f32_16x16x32_bf16 v[90:93], v[178:181], v[186:189], v[90:93]
	v_mfma_f32_16x16x32_bf16 v[86:89], v[146:149], v[212:215], v[86:89]
	v_mfma_f32_16x16x32_bf16 v[82:85], v[178:181], v[212:215], v[82:85]
	v_mfma_f32_16x16x32_bf16 v[78:81], v[146:149], v[220:223], v[78:81]
	v_mfma_f32_16x16x32_bf16 v[74:77], v[178:181], v[220:223], v[74:77]
	v_mfma_f32_16x16x32_bf16 v[70:73], v[146:149], v[228:231], v[70:73]
	v_mfma_f32_16x16x32_bf16 v[66:69], v[178:181], v[228:231], v[66:69]
	v_mfma_f32_16x16x32_bf16 v[94:97], v[150:153], v[208:211], v[94:97]
	v_mfma_f32_16x16x32_bf16 v[90:93], v[182:185], v[208:211], v[90:93]
	v_mfma_f32_16x16x32_bf16 v[86:89], v[150:153], v[216:219], v[86:89]
	v_mfma_f32_16x16x32_bf16 v[82:85], v[182:185], v[216:219], v[82:85]
	v_mfma_f32_16x16x32_bf16 v[78:81], v[150:153], v[224:227], v[78:81]
	v_mfma_f32_16x16x32_bf16 v[74:77], v[182:185], v[224:227], v[74:77]
	v_mfma_f32_16x16x32_bf16 v[70:73], v[150:153], v[232:235], v[70:73]
	v_mfma_f32_16x16x32_bf16 v[66:69], v[182:185], v[232:235], v[66:69]
	s_barrier
	s_setprio 0
	s_add_i32 s46, s48, s80
	v_lshl_add_u64 v[236:237], v[236:237], 0, s[42:43]
	s_mov_b32 m0, s46
	ds_read_b128 v[186:189], v207 offset:49152
	ds_read_b128 v[208:211], v207 offset:50176
	ds_read_b128 v[212:215], v207 offset:51200
	ds_read_b128 v[216:219], v207 offset:52224
	ds_read_b128 v[220:223], v207 offset:53248
	ds_read_b128 v[224:227], v207 offset:54272
	ds_read_b128 v[228:231], v207 offset:55296
	ds_read_b128 v[232:235], v207 offset:56320
	global_load_lds_dwordx4 v[236:237], off
	v_lshl_add_u64 v[236:237], v[242:243], 0, s[42:43]
	s_add_i32 m0, s46, 0x2000
	s_add_i32 s46, s49, s80
	global_load_lds_dwordx4 v[236:237], off
	v_lshl_add_u64 v[236:237], v[244:245], 0, s[42:43]
	s_mov_b32 m0, s46
	s_nop 0
	global_load_lds_dwordx4 v[236:237], off
	v_lshl_add_u64 v[236:237], v[246:247], 0, s[42:43]
	s_add_i32 m0, s46, 0x2000
	s_nop 0
	global_load_lds_dwordx4 v[236:237], off
	v_lshl_add_u64 v[236:237], v[248:249], 0, s[42:43]
	s_mov_b32 m0, s85
	s_nop 0
	global_load_lds_dwordx4 v[236:237], off
	v_lshl_add_u64 v[236:237], v[250:251], 0, s[42:43]
	s_mov_b32 m0, s86
	s_nop 0
	global_load_lds_dwordx4 v[236:237], off
	s_setprio 1
	s_waitcnt lgkmcnt(7)
	v_mfma_f32_16x16x32_bf16 v[62:65], v[130:133], v[186:189], v[62:65]
	v_mfma_f32_16x16x32_bf16 v[58:61], v[138:141], v[186:189], v[58:61]
	s_waitcnt lgkmcnt(5)
	v_mfma_f32_16x16x32_bf16 v[54:57], v[130:133], v[212:215], v[54:57]
	v_mfma_f32_16x16x32_bf16 v[50:53], v[138:141], v[212:215], v[50:53]
	s_waitcnt vmcnt(8)
	s_waitcnt lgkmcnt(0)
	s_barrier
	v_mfma_f32_16x16x32_bf16 v[46:49], v[130:133], v[220:223], v[46:49]
	v_mfma_f32_16x16x32_bf16 v[42:45], v[138:141], v[220:223], v[42:45]
	v_mfma_f32_16x16x32_bf16 v[38:41], v[130:133], v[228:231], v[38:41]
	v_mfma_f32_16x16x32_bf16 v[34:37], v[138:141], v[228:231], v[34:37]
	v_mfma_f32_16x16x32_bf16 v[62:65], v[134:137], v[208:211], v[62:65]
	v_mfma_f32_16x16x32_bf16 v[58:61], v[142:145], v[208:211], v[58:61]
	v_mfma_f32_16x16x32_bf16 v[54:57], v[134:137], v[216:219], v[54:57]
	v_mfma_f32_16x16x32_bf16 v[50:53], v[142:145], v[216:219], v[50:53]
	v_mfma_f32_16x16x32_bf16 v[46:49], v[134:137], v[224:227], v[46:49]
	v_mfma_f32_16x16x32_bf16 v[42:45], v[142:145], v[224:227], v[42:45]
	v_mfma_f32_16x16x32_bf16 v[38:41], v[134:137], v[232:235], v[38:41]
	v_mfma_f32_16x16x32_bf16 v[34:37], v[142:145], v[232:235], v[34:37]
	s_setprio 0
	s_setprio 1
	v_mfma_f32_16x16x32_bf16 v[30:33], v[146:149], v[186:189], v[30:33]
	v_mfma_f32_16x16x32_bf16 v[26:29], v[178:181], v[186:189], v[26:29]
	v_mfma_f32_16x16x32_bf16 v[22:25], v[146:149], v[212:215], v[22:25]
	v_mfma_f32_16x16x32_bf16 v[18:21], v[178:181], v[212:215], v[18:21]
	v_mfma_f32_16x16x32_bf16 v[14:17], v[146:149], v[220:223], v[14:17]
	v_mfma_f32_16x16x32_bf16 v[10:13], v[178:181], v[220:223], v[10:13]
	v_mfma_f32_16x16x32_bf16 v[6:9], v[146:149], v[228:231], v[6:9]
	v_mfma_f32_16x16x32_bf16 v[2:5], v[178:181], v[228:231], v[2:5]
	v_mfma_f32_16x16x32_bf16 v[30:33], v[150:153], v[208:211], v[30:33]
	v_mfma_f32_16x16x32_bf16 v[26:29], v[182:185], v[208:211], v[26:29]
	v_mfma_f32_16x16x32_bf16 v[22:25], v[150:153], v[216:219], v[22:25]
	v_mfma_f32_16x16x32_bf16 v[18:21], v[182:185], v[216:219], v[18:21]
	v_mfma_f32_16x16x32_bf16 v[14:17], v[150:153], v[224:227], v[14:17]
	v_mfma_f32_16x16x32_bf16 v[10:13], v[182:185], v[224:227], v[10:13]
	v_mfma_f32_16x16x32_bf16 v[6:9], v[150:153], v[232:235], v[6:9]
	v_mfma_f32_16x16x32_bf16 v[2:5], v[182:185], v[232:235], v[2:5]
	s_barrier
	s_setprio 0
	s_add_u32 s72, s72, 0x100
	s_addc_u32 s73, s73, 0
	s_add_u32 s91, s91, 0x100
	s_addc_u32 s92, s92, 0
	s_cmp_ge_u32 s93, s84
	s_mov_b32 s60, s93
	s_cbranch_scc0 .LBB0_819
	s_and_b64 vcc, exec, s[18:19]
	s_cbranch_vccz .LBB0_822
	s_barrier

.LBB0_903:
	s_add_u32 s46, s66, 0xfff80080
	s_addc_u32 s47, s67, -1
	s_add_i32 s48, 0, 0x10000
	s_cmp_eq_u32 s84, 28
	s_cselect_b32 s69, s17, s47
	s_cselect_b32 s68, s64, s46
	s_cselect_b32 s61, s13, s83
	s_cselect_b32 s60, s81, s82
	s_add_i32 s49, 0, 0x14000
	v_add_u32_e32 v142, s48, v186
	v_add_u32_e32 v164, s49, v186
	ds_read_b128 v[130:133], v142
	ds_read_b128 v[134:137], v142 offset:1024
	ds_read_b128 v[138:141], v142 offset:2048
	ds_read_b128 v[142:145], v142 offset:3072
	ds_read_b128 v[146:149], v164
	ds_read_b128 v[160:163], v164 offset:1024
	ds_read_b128 v[178:181], v164 offset:2048
	ds_read_b128 v[182:185], v164 offset:3072
	v_lshl_add_u64 v[164:165], s[66:67], 0, v[156:157]
	s_add_i32 m0, s74, 0xc000
	ds_read_b128 v[206:209], v188
	ds_read_b128 v[210:213], v188 offset:1024
	ds_read_b128 v[214:217], v188 offset:2048
	ds_read_b128 v[218:221], v188 offset:3072
	ds_read_b128 v[222:225], v188 offset:4096
	ds_read_b128 v[226:229], v188 offset:5120
	ds_read_b128 v[230:233], v188 offset:6144
	ds_read_b128 v[234:237], v188 offset:7168
	global_load_lds_dwordx4 v[164:165], off
	v_lshl_add_u64 v[164:165], s[66:67], 0, v[158:159]
	s_add_i32 m0, s74, 0xe000
	s_nop 0
	global_load_lds_dwordx4 v[164:165], off
	s_setprio 1
	s_waitcnt lgkmcnt(7)
	v_mfma_f32_16x16x32_bf16 v[126:129], v[130:133], v[206:209], v[126:129]
	v_mfma_f32_16x16x32_bf16 v[122:125], v[138:141], v[206:209], v[122:125]
	s_waitcnt lgkmcnt(5)
	v_mfma_f32_16x16x32_bf16 v[118:121], v[130:133], v[214:217], v[118:121]
	v_mfma_f32_16x16x32_bf16 v[110:113], v[138:141], v[214:217], v[110:113]
	s_waitcnt vmcnt(8)
	s_waitcnt lgkmcnt(0)
	s_barrier
	v_mfma_f32_16x16x32_bf16 v[94:97], v[130:133], v[222:225], v[94:97]
	v_mfma_f32_16x16x32_bf16 v[90:93], v[138:141], v[222:225], v[90:93]
	v_mfma_f32_16x16x32_bf16 v[82:85], v[130:133], v[230:233], v[82:85]
	v_mfma_f32_16x16x32_bf16 v[74:77], v[138:141], v[230:233], v[74:77]
	v_mfma_f32_16x16x32_bf16 v[126:129], v[134:137], v[210:213], v[126:129]
	v_mfma_f32_16x16x32_bf16 v[122:125], v[142:145], v[210:213], v[122:125]
	v_mfma_f32_16x16x32_bf16 v[118:121], v[134:137], v[218:221], v[118:121]
	v_mfma_f32_16x16x32_bf16 v[110:113], v[142:145], v[218:221], v[110:113]
	v_mfma_f32_16x16x32_bf16 v[94:97], v[134:137], v[226:229], v[94:97]
	v_mfma_f32_16x16x32_bf16 v[90:93], v[142:145], v[226:229], v[90:93]
	v_mfma_f32_16x16x32_bf16 v[82:85], v[134:137], v[234:237], v[82:85]
	v_mfma_f32_16x16x32_bf16 v[74:77], v[142:145], v[234:237], v[74:77]
	s_setprio 0
	s_setprio 1
	v_mfma_f32_16x16x32_bf16 v[114:117], v[146:149], v[206:209], v[114:117]
	v_mfma_f32_16x16x32_bf16 v[106:109], v[178:181], v[206:209], v[106:109]
	v_mfma_f32_16x16x32_bf16 v[102:105], v[146:149], v[214:217], v[102:105]
	v_mfma_f32_16x16x32_bf16 v[98:101], v[178:181], v[214:217], v[98:101]
	v_mfma_f32_16x16x32_bf16 v[86:89], v[146:149], v[222:225], v[86:89]
	v_mfma_f32_16x16x32_bf16 v[78:81], v[178:181], v[222:225], v[78:81]
	v_mfma_f32_16x16x32_bf16 v[70:73], v[146:149], v[230:233], v[70:73]
	v_mfma_f32_16x16x32_bf16 v[66:69], v[178:181], v[230:233], v[66:69]
	v_mfma_f32_16x16x32_bf16 v[114:117], v[160:163], v[210:213], v[114:117]
	v_mfma_f32_16x16x32_bf16 v[106:109], v[182:185], v[210:213], v[106:109]
	v_mfma_f32_16x16x32_bf16 v[102:105], v[160:163], v[218:221], v[102:105]
	v_mfma_f32_16x16x32_bf16 v[98:101], v[182:185], v[218:221], v[98:101]
	v_mfma_f32_16x16x32_bf16 v[86:89], v[160:163], v[226:229], v[86:89]
	v_mfma_f32_16x16x32_bf16 v[78:81], v[182:185], v[226:229], v[78:81]
	v_mfma_f32_16x16x32_bf16 v[70:73], v[160:163], v[234:237], v[70:73]
	v_mfma_f32_16x16x32_bf16 v[66:69], v[182:185], v[234:237], v[66:69]
	s_barrier
	s_setprio 0
	s_add_i32 s46, s48, s73
	v_lshl_add_u64 v[164:165], s[60:61], 0, v[166:167]
	s_mov_b32 m0, s46
	ds_read_b128 v[206:209], v188 offset:16384
	ds_read_b128 v[210:213], v188 offset:17408
	ds_read_b128 v[214:217], v188 offset:18432
	ds_read_b128 v[218:221], v188 offset:19456
	ds_read_b128 v[222:225], v188 offset:20480
	ds_read_b128 v[226:229], v188 offset:21504
	ds_read_b128 v[230:233], v188 offset:22528
	ds_read_b128 v[234:237], v188 offset:23552
	global_load_lds_dwordx4 v[164:165], off
	s_add_i32 m0, s46, 0x2000
	s_add_u32 s46, s60, 0x80000
	v_lshl_add_u64 v[242:243], s[60:61], 0, v[154:155]
	s_addc_u32 s47, s61, 0
	s_add_i32 s48, s49, s73
	global_load_lds_dwordx4 v[242:243], off
	v_lshl_add_u64 v[244:245], s[46:47], 0, v[166:167]
	s_mov_b32 m0, s48
	v_lshl_add_u64 v[246:247], s[68:69], 0, v[152:153]
	global_load_lds_dwordx4 v[244:245], off
	v_lshl_add_u64 v[244:245], s[46:47], 0, v[154:155]
	s_add_i32 m0, s48, 0x2000
	s_nop 0
	global_load_lds_dwordx4 v[244:245], off
	v_lshl_add_u64 v[244:245], s[68:69], 0, v[150:151]
	s_mov_b32 m0, s74
	s_nop 0
	global_load_lds_dwordx4 v[244:245], off
	s_mov_b32 m0, s75
	s_nop 0
	global_load_lds_dwordx4 v[246:247], off
	s_setprio 1
	s_waitcnt lgkmcnt(7)
	v_mfma_f32_16x16x32_bf16 v[62:65], v[130:133], v[206:209], v[62:65]
	v_mfma_f32_16x16x32_bf16 v[58:61], v[138:141], v[206:209], v[58:61]
	s_waitcnt lgkmcnt(5)
	v_mfma_f32_16x16x32_bf16 v[50:53], v[130:133], v[214:217], v[50:53]
	v_mfma_f32_16x16x32_bf16 v[42:45], v[138:141], v[214:217], v[42:45]
	s_waitcnt vmcnt(8)
	s_waitcnt lgkmcnt(0)
	s_barrier
	v_mfma_f32_16x16x32_bf16 v[34:37], v[130:133], v[222:225], v[34:37]
	v_mfma_f32_16x16x32_bf16 v[26:29], v[138:141], v[222:225], v[26:29]
	v_mfma_f32_16x16x32_bf16 v[18:21], v[130:133], v[230:233], v[18:21]
	v_mfma_f32_16x16x32_bf16 v[10:13], v[138:141], v[230:233], v[10:13]
	v_mfma_f32_16x16x32_bf16 v[62:65], v[134:137], v[210:213], v[62:65]
	v_mfma_f32_16x16x32_bf16 v[58:61], v[142:145], v[210:213], v[58:61]
	v_mfma_f32_16x16x32_bf16 v[50:53], v[134:137], v[218:221], v[50:53]
	v_mfma_f32_16x16x32_bf16 v[42:45], v[142:145], v[218:221], v[42:45]
	v_mfma_f32_16x16x32_bf16 v[34:37], v[134:137], v[226:229], v[34:37]
	v_mfma_f32_16x16x32_bf16 v[26:29], v[142:145], v[226:229], v[26:29]
	v_mfma_f32_16x16x32_bf16 v[18:21], v[134:137], v[234:237], v[18:21]
	v_mfma_f32_16x16x32_bf16 v[10:13], v[142:145], v[234:237], v[10:13]
	s_setprio 0
	s_setprio 1
	v_mfma_f32_16x16x32_bf16 v[54:57], v[146:149], v[206:209], v[54:57]
	v_mfma_f32_16x16x32_bf16 v[46:49], v[178:181], v[206:209], v[46:49]
	v_mfma_f32_16x16x32_bf16 v[38:41], v[146:149], v[214:217], v[38:41]
	v_mfma_f32_16x16x32_bf16 v[30:33], v[178:181], v[214:217], v[30:33]
	v_mfma_f32_16x16x32_bf16 v[22:25], v[146:149], v[222:225], v[22:25]
	v_mfma_f32_16x16x32_bf16 v[14:17], v[178:181], v[222:225], v[14:17]
	v_mfma_f32_16x16x32_bf16 v[6:9], v[146:149], v[230:233], v[6:9]
	v_mfma_f32_16x16x32_bf16 v[2:5], v[178:181], v[230:233], v[2:5]
	v_mfma_f32_16x16x32_bf16 v[54:57], v[160:163], v[210:213], v[54:57]
	v_mfma_f32_16x16x32_bf16 v[46:49], v[182:185], v[210:213], v[46:49]
	v_mfma_f32_16x16x32_bf16 v[38:41], v[160:163], v[218:221], v[38:41]
	v_mfma_f32_16x16x32_bf16 v[30:33], v[182:185], v[218:221], v[30:33]
	v_mfma_f32_16x16x32_bf16 v[22:25], v[160:163], v[226:229], v[22:25]
	v_mfma_f32_16x16x32_bf16 v[14:17], v[182:185], v[226:229], v[14:17]
	v_mfma_f32_16x16x32_bf16 v[6:9], v[160:163], v[234:237], v[6:9]
	v_mfma_f32_16x16x32_bf16 v[2:5], v[182:185], v[234:237], v[2:5]
	s_barrier
	s_setprio 0
	s_add_i32 s48, 0, 0x18000
	s_add_i32 s49, 0, 0x1c000
	v_add_u32_e32 v142, s48, v186
	v_add_u32_e32 v182, s49, v186
	ds_read_b128 v[130:133], v142
	ds_read_b128 v[134:137], v142 offset:1024
	ds_read_b128 v[138:141], v142 offset:2048
	ds_read_b128 v[142:145], v142 offset:3072
	ds_read_b128 v[146:149], v182
	ds_read_b128 v[160:163], v182 offset:1024
	ds_read_b128 v[178:181], v182 offset:2048
	ds_read_b128 v[182:185], v182 offset:3072
	s_add_u32 s46, s68, 0x80000
	s_addc_u32 s47, s69, 0
	s_mov_b32 m0, s76
	v_lshl_add_u64 v[248:249], s[46:47], 0, v[150:151]
	ds_read_b128 v[206:209], v188 offset:32768
	ds_read_b128 v[210:213], v188 offset:33792
	ds_read_b128 v[214:217], v188 offset:34816
	ds_read_b128 v[218:221], v188 offset:35840
	ds_read_b128 v[222:225], v188 offset:36864
	ds_read_b128 v[226:229], v188 offset:37888
	ds_read_b128 v[230:233], v188 offset:38912
	ds_read_b128 v[234:237], v188 offset:39936
	global_load_lds_dwordx4 v[248:249], off
	v_lshl_add_u64 v[248:249], s[46:47], 0, v[152:153]
	s_mov_b32 m0, s77
	s_nop 0
	global_load_lds_dwordx4 v[248:249], off
	s_setprio 1
	s_waitcnt lgkmcnt(7)
	v_mfma_f32_16x16x32_bf16 v[126:129], v[130:133], v[206:209], v[126:129]
	v_mfma_f32_16x16x32_bf16 v[122:125], v[138:141], v[206:209], v[122:125]
	s_waitcnt lgkmcnt(5)
	v_mfma_f32_16x16x32_bf16 v[118:121], v[130:133], v[214:217], v[118:121]
	v_mfma_f32_16x16x32_bf16 v[110:113], v[138:141], v[214:217], v[110:113]
	s_waitcnt vmcnt(8)
	s_waitcnt lgkmcnt(0)
	s_barrier
	v_mfma_f32_16x16x32_bf16 v[94:97], v[130:133], v[222:225], v[94:97]
	v_mfma_f32_16x16x32_bf16 v[90:93], v[138:141], v[222:225], v[90:93]
	v_mfma_f32_16x16x32_bf16 v[82:85], v[130:133], v[230:233], v[82:85]
	v_mfma_f32_16x16x32_bf16 v[74:77], v[138:141], v[230:233], v[74:77]
	v_mfma_f32_16x16x32_bf16 v[126:129], v[134:137], v[210:213], v[126:129]
	v_mfma_f32_16x16x32_bf16 v[122:125], v[142:145], v[210:213], v[122:125]
	v_mfma_f32_16x16x32_bf16 v[118:121], v[134:137], v[218:221], v[118:121]
	v_mfma_f32_16x16x32_bf16 v[110:113], v[142:145], v[218:221], v[110:113]
	v_mfma_f32_16x16x32_bf16 v[94:97], v[134:137], v[226:229], v[94:97]
	v_mfma_f32_16x16x32_bf16 v[90:93], v[142:145], v[226:229], v[90:93]
	v_mfma_f32_16x16x32_bf16 v[82:85], v[134:137], v[234:237], v[82:85]
	v_mfma_f32_16x16x32_bf16 v[74:77], v[142:145], v[234:237], v[74:77]
	s_setprio 0
	s_setprio 1
	v_mfma_f32_16x16x32_bf16 v[114:117], v[146:149], v[206:209], v[114:117]
	v_mfma_f32_16x16x32_bf16 v[106:109], v[178:181], v[206:209], v[106:109]
	v_mfma_f32_16x16x32_bf16 v[102:105], v[146:149], v[214:217], v[102:105]
	v_mfma_f32_16x16x32_bf16 v[98:101], v[178:181], v[214:217], v[98:101]
	v_mfma_f32_16x16x32_bf16 v[86:89], v[146:149], v[222:225], v[86:89]
	v_mfma_f32_16x16x32_bf16 v[78:81], v[178:181], v[222:225], v[78:81]
	v_mfma_f32_16x16x32_bf16 v[70:73], v[146:149], v[230:233], v[70:73]
	v_mfma_f32_16x16x32_bf16 v[66:69], v[178:181], v[230:233], v[66:69]
	v_mfma_f32_16x16x32_bf16 v[114:117], v[160:163], v[210:213], v[114:117]
	v_mfma_f32_16x16x32_bf16 v[106:109], v[182:185], v[210:213], v[106:109]
	v_mfma_f32_16x16x32_bf16 v[102:105], v[160:163], v[218:221], v[102:105]
	v_mfma_f32_16x16x32_bf16 v[98:101], v[182:185], v[218:221], v[98:101]
	v_mfma_f32_16x16x32_bf16 v[86:89], v[160:163], v[226:229], v[86:89]
	v_mfma_f32_16x16x32_bf16 v[78:81], v[182:185], v[226:229], v[78:81]
	v_mfma_f32_16x16x32_bf16 v[70:73], v[160:163], v[234:237], v[70:73]
	v_mfma_f32_16x16x32_bf16 v[66:69], v[182:185], v[234:237], v[66:69]
	s_barrier
	s_setprio 0
	s_add_i32 s46, s48, s73
	v_lshl_add_u64 v[164:165], v[164:165], 0, s[42:43]
	s_mov_b32 m0, s46
	ds_read_b128 v[206:209], v188 offset:49152
	ds_read_b128 v[210:213], v188 offset:50176
	ds_read_b128 v[214:217], v188 offset:51200
	ds_read_b128 v[218:221], v188 offset:52224
	ds_read_b128 v[222:225], v188 offset:53248
	ds_read_b128 v[226:229], v188 offset:54272
	ds_read_b128 v[230:233], v188 offset:55296
	ds_read_b128 v[234:237], v188 offset:56320
	global_load_lds_dwordx4 v[164:165], off
	s_add_i32 m0, s46, 0x2000
	s_add_u32 s46, s60, 0x80080
	v_lshl_add_u64 v[164:165], v[242:243], 0, s[42:43]
	s_addc_u32 s47, s61, 0
	s_add_i32 s48, s49, s73
	global_load_lds_dwordx4 v[164:165], off
	v_lshl_add_u64 v[164:165], s[46:47], 0, v[166:167]
	s_mov_b32 m0, s48
	s_nop 0
	global_load_lds_dwordx4 v[164:165], off
	v_lshl_add_u64 v[164:165], s[46:47], 0, v[154:155]
	s_add_i32 m0, s48, 0x2000
	s_nop 0
	global_load_lds_dwordx4 v[164:165], off
	v_lshl_add_u64 v[164:165], v[244:245], 0, s[42:43]
	s_mov_b32 m0, s78
	s_nop 0
	global_load_lds_dwordx4 v[164:165], off
	v_lshl_add_u64 v[164:165], v[246:247], 0, s[42:43]
	s_mov_b32 m0, s79
	s_nop 0
	global_load_lds_dwordx4 v[164:165], off
	s_setprio 1
	s_waitcnt lgkmcnt(7)
	v_mfma_f32_16x16x32_bf16 v[62:65], v[130:133], v[206:209], v[62:65]
	v_mfma_f32_16x16x32_bf16 v[58:61], v[138:141], v[206:209], v[58:61]
	s_waitcnt lgkmcnt(5)
	v_mfma_f32_16x16x32_bf16 v[50:53], v[130:133], v[214:217], v[50:53]
	v_mfma_f32_16x16x32_bf16 v[42:45], v[138:141], v[214:217], v[42:45]
	s_waitcnt vmcnt(8)
	s_waitcnt lgkmcnt(0)
	s_barrier
	v_mfma_f32_16x16x32_bf16 v[34:37], v[130:133], v[222:225], v[34:37]
	v_mfma_f32_16x16x32_bf16 v[26:29], v[138:141], v[222:225], v[26:29]
	v_mfma_f32_16x16x32_bf16 v[18:21], v[130:133], v[230:233], v[18:21]
	v_mfma_f32_16x16x32_bf16 v[10:13], v[138:141], v[230:233], v[10:13]
	v_mfma_f32_16x16x32_bf16 v[62:65], v[134:137], v[210:213], v[62:65]
	v_mfma_f32_16x16x32_bf16 v[58:61], v[142:145], v[210:213], v[58:61]
	v_mfma_f32_16x16x32_bf16 v[50:53], v[134:137], v[218:221], v[50:53]
	v_mfma_f32_16x16x32_bf16 v[42:45], v[142:145], v[218:221], v[42:45]
	v_mfma_f32_16x16x32_bf16 v[34:37], v[134:137], v[226:229], v[34:37]
	v_mfma_f32_16x16x32_bf16 v[26:29], v[142:145], v[226:229], v[26:29]
	v_mfma_f32_16x16x32_bf16 v[18:21], v[134:137], v[234:237], v[18:21]
	v_mfma_f32_16x16x32_bf16 v[10:13], v[142:145], v[234:237], v[10:13]
	s_setprio 0
	s_setprio 1
	v_mfma_f32_16x16x32_bf16 v[54:57], v[146:149], v[206:209], v[54:57]
	v_mfma_f32_16x16x32_bf16 v[46:49], v[178:181], v[206:209], v[46:49]
	v_mfma_f32_16x16x32_bf16 v[38:41], v[146:149], v[214:217], v[38:41]
	v_mfma_f32_16x16x32_bf16 v[30:33], v[178:181], v[214:217], v[30:33]
	v_mfma_f32_16x16x32_bf16 v[22:25], v[146:149], v[222:225], v[22:25]
	v_mfma_f32_16x16x32_bf16 v[14:17], v[178:181], v[222:225], v[14:17]
	v_mfma_f32_16x16x32_bf16 v[6:9], v[146:149], v[230:233], v[6:9]
	v_mfma_f32_16x16x32_bf16 v[2:5], v[178:181], v[230:233], v[2:5]
	v_mfma_f32_16x16x32_bf16 v[54:57], v[160:163], v[210:213], v[54:57]
	v_mfma_f32_16x16x32_bf16 v[46:49], v[182:185], v[210:213], v[46:49]
	v_mfma_f32_16x16x32_bf16 v[38:41], v[160:163], v[218:221], v[38:41]
	v_mfma_f32_16x16x32_bf16 v[30:33], v[182:185], v[218:221], v[30:33]
	v_mfma_f32_16x16x32_bf16 v[22:25], v[160:163], v[226:229], v[22:25]
	v_mfma_f32_16x16x32_bf16 v[14:17], v[182:185], v[226:229], v[14:17]
	v_mfma_f32_16x16x32_bf16 v[6:9], v[160:163], v[234:237], v[6:9]
	v_mfma_f32_16x16x32_bf16 v[2:5], v[182:185], v[234:237], v[2:5]
	s_barrier
	s_setprio 0
	s_add_i32 s84, s84, 2
	s_add_u32 s66, s66, 0x100
	s_addc_u32 s67, s67, 0
	s_add_u32 s82, s82, 0x100
	s_addc_u32 s83, s83, 0
	s_cmp_gt_u32 s84, 29
	s_cbranch_scc0 .LBB0_903
	s_and_b64 vcc, exec, s[10:11]
	s_cbranch_vccz .LBB0_906
	s_barrier

.LBB0_1035:
	s_add_u32 s46, s64, 0xfff80080
	s_addc_u32 s47, s65, -1
	s_add_i32 s48, 0, 0x10000
	s_cmp_eq_u32 s84, 28
	s_cselect_b32 s67, s17, s47
	s_cselect_b32 s66, s80, s46
	v_add_u32_e32 v140, s48, v142
	s_cselect_b32 s61, s13, s83
	s_cselect_b32 s60, s81, s82
	s_add_i32 s49, 0, 0x14000
	ds_read_b128 v[146:149], v140
	ds_read_b128 v[150:153], v140 offset:1024
	ds_read_b128 v[154:157], v140 offset:2048
	ds_read_b128 v[158:161], v140 offset:3072
	v_add_u32_e32 v140, s49, v142
	ds_read_b128 v[162:165], v140
	ds_read_b128 v[178:181], v140 offset:1024
	ds_read_b128 v[182:185], v140 offset:2048
	ds_read_b128 v[186:189], v140 offset:3072
	v_lshl_add_u64 v[140:141], s[64:65], 0, v[136:137]
	s_add_i32 m0, s23, 0xc000
	ds_read_b128 v[206:209], v144
	ds_read_b128 v[210:213], v144 offset:1024
	ds_read_b128 v[214:217], v144 offset:2048
	ds_read_b128 v[218:221], v144 offset:3072
	ds_read_b128 v[222:225], v144 offset:4096
	ds_read_b128 v[226:229], v144 offset:5120
	ds_read_b128 v[230:233], v144 offset:6144
	ds_read_b128 v[234:237], v144 offset:7168
	global_load_lds_dwordx4 v[140:141], off
	v_lshl_add_u64 v[140:141], s[64:65], 0, v[138:139]
	s_add_i32 m0, s23, 0xe000
	s_nop 0
	global_load_lds_dwordx4 v[140:141], off
	s_setprio 1
	s_waitcnt lgkmcnt(7)
	v_mfma_f32_16x16x32_bf16 v[126:129], v[146:149], v[206:209], v[126:129]
	v_mfma_f32_16x16x32_bf16 v[122:125], v[154:157], v[206:209], v[122:125]
	s_waitcnt lgkmcnt(5)
	v_mfma_f32_16x16x32_bf16 v[110:113], v[146:149], v[214:217], v[110:113]
	v_mfma_f32_16x16x32_bf16 v[106:109], v[154:157], v[214:217], v[106:109]
	s_waitcnt vmcnt(8)
	s_waitcnt lgkmcnt(0)
	s_barrier
	v_mfma_f32_16x16x32_bf16 v[94:97], v[146:149], v[222:225], v[94:97]
	v_mfma_f32_16x16x32_bf16 v[90:93], v[154:157], v[222:225], v[90:93]
	v_mfma_f32_16x16x32_bf16 v[78:81], v[146:149], v[230:233], v[78:81]
	v_mfma_f32_16x16x32_bf16 v[74:77], v[154:157], v[230:233], v[74:77]
	v_mfma_f32_16x16x32_bf16 v[126:129], v[150:153], v[210:213], v[126:129]
	v_mfma_f32_16x16x32_bf16 v[122:125], v[158:161], v[210:213], v[122:125]
	v_mfma_f32_16x16x32_bf16 v[110:113], v[150:153], v[218:221], v[110:113]
	v_mfma_f32_16x16x32_bf16 v[106:109], v[158:161], v[218:221], v[106:109]
	v_mfma_f32_16x16x32_bf16 v[94:97], v[150:153], v[226:229], v[94:97]
	v_mfma_f32_16x16x32_bf16 v[90:93], v[158:161], v[226:229], v[90:93]
	v_mfma_f32_16x16x32_bf16 v[78:81], v[150:153], v[234:237], v[78:81]
	v_mfma_f32_16x16x32_bf16 v[74:77], v[158:161], v[234:237], v[74:77]
	s_setprio 0
	s_setprio 1
	v_mfma_f32_16x16x32_bf16 v[118:121], v[162:165], v[206:209], v[118:121]
	v_mfma_f32_16x16x32_bf16 v[114:117], v[182:185], v[206:209], v[114:117]
	v_mfma_f32_16x16x32_bf16 v[102:105], v[162:165], v[214:217], v[102:105]
	v_mfma_f32_16x16x32_bf16 v[98:101], v[182:185], v[214:217], v[98:101]
	v_mfma_f32_16x16x32_bf16 v[86:89], v[162:165], v[222:225], v[86:89]
	v_mfma_f32_16x16x32_bf16 v[82:85], v[182:185], v[222:225], v[82:85]
	v_mfma_f32_16x16x32_bf16 v[70:73], v[162:165], v[230:233], v[70:73]
	v_mfma_f32_16x16x32_bf16 v[66:69], v[182:185], v[230:233], v[66:69]
	v_mfma_f32_16x16x32_bf16 v[118:121], v[178:181], v[210:213], v[118:121]
	v_mfma_f32_16x16x32_bf16 v[114:117], v[186:189], v[210:213], v[114:117]
	v_mfma_f32_16x16x32_bf16 v[102:105], v[178:181], v[218:221], v[102:105]
	v_mfma_f32_16x16x32_bf16 v[98:101], v[186:189], v[218:221], v[98:101]
	v_mfma_f32_16x16x32_bf16 v[86:89], v[178:181], v[226:229], v[86:89]
	v_mfma_f32_16x16x32_bf16 v[82:85], v[186:189], v[226:229], v[82:85]
	v_mfma_f32_16x16x32_bf16 v[70:73], v[178:181], v[234:237], v[70:73]
	v_mfma_f32_16x16x32_bf16 v[66:69], v[186:189], v[234:237], v[66:69]
	s_barrier
	s_setprio 0
	s_add_i32 s46, s48, s72
	v_lshl_add_u64 v[140:141], s[60:61], 0, v[166:167]
	s_mov_b32 m0, s46
	ds_read_b128 v[206:209], v144 offset:16384
	ds_read_b128 v[210:213], v144 offset:17408
	ds_read_b128 v[214:217], v144 offset:18432
	ds_read_b128 v[218:221], v144 offset:19456
	ds_read_b128 v[222:225], v144 offset:20480
	ds_read_b128 v[226:229], v144 offset:21504
	ds_read_b128 v[230:233], v144 offset:22528
	ds_read_b128 v[234:237], v144 offset:23552
	global_load_lds_dwordx4 v[140:141], off
	s_add_i32 m0, s46, 0x2000
	s_add_u32 s46, s60, 0x80000
	v_lshl_add_u64 v[242:243], s[60:61], 0, v[134:135]
	s_addc_u32 s47, s61, 0
	s_add_i32 s48, s49, s72
	global_load_lds_dwordx4 v[242:243], off
	v_lshl_add_u64 v[244:245], s[46:47], 0, v[166:167]
	s_mov_b32 m0, s48
	v_lshl_add_u64 v[246:247], s[66:67], 0, v[132:133]
	global_load_lds_dwordx4 v[244:245], off
	v_lshl_add_u64 v[244:245], s[46:47], 0, v[134:135]
	s_add_i32 m0, s48, 0x2000
	s_nop 0
	global_load_lds_dwordx4 v[244:245], off
	v_lshl_add_u64 v[244:245], s[66:67], 0, v[130:131]
	s_mov_b32 m0, s23
	s_nop 0
	global_load_lds_dwordx4 v[244:245], off
	s_mov_b32 m0, s73
	s_nop 0
	global_load_lds_dwordx4 v[246:247], off
	s_setprio 1
	s_waitcnt lgkmcnt(7)
	v_mfma_f32_16x16x32_bf16 v[62:65], v[146:149], v[206:209], v[62:65]
	v_mfma_f32_16x16x32_bf16 v[58:61], v[154:157], v[206:209], v[58:61]
	s_waitcnt lgkmcnt(5)
	v_mfma_f32_16x16x32_bf16 v[46:49], v[146:149], v[214:217], v[46:49]
	v_mfma_f32_16x16x32_bf16 v[42:45], v[154:157], v[214:217], v[42:45]
	s_waitcnt vmcnt(8)
	s_waitcnt lgkmcnt(0)
	s_barrier
	v_mfma_f32_16x16x32_bf16 v[30:33], v[146:149], v[222:225], v[30:33]
	v_mfma_f32_16x16x32_bf16 v[26:29], v[154:157], v[222:225], v[26:29]
	v_mfma_f32_16x16x32_bf16 v[14:17], v[146:149], v[230:233], v[14:17]
	v_mfma_f32_16x16x32_bf16 v[10:13], v[154:157], v[230:233], v[10:13]
	v_mfma_f32_16x16x32_bf16 v[62:65], v[150:153], v[210:213], v[62:65]
	v_mfma_f32_16x16x32_bf16 v[58:61], v[158:161], v[210:213], v[58:61]
	v_mfma_f32_16x16x32_bf16 v[46:49], v[150:153], v[218:221], v[46:49]
	v_mfma_f32_16x16x32_bf16 v[42:45], v[158:161], v[218:221], v[42:45]
	v_mfma_f32_16x16x32_bf16 v[30:33], v[150:153], v[226:229], v[30:33]
	v_mfma_f32_16x16x32_bf16 v[26:29], v[158:161], v[226:229], v[26:29]
	v_mfma_f32_16x16x32_bf16 v[14:17], v[150:153], v[234:237], v[14:17]
	v_mfma_f32_16x16x32_bf16 v[10:13], v[158:161], v[234:237], v[10:13]
	s_setprio 0
	s_setprio 1
	v_mfma_f32_16x16x32_bf16 v[54:57], v[162:165], v[206:209], v[54:57]
	v_mfma_f32_16x16x32_bf16 v[50:53], v[182:185], v[206:209], v[50:53]
	v_mfma_f32_16x16x32_bf16 v[38:41], v[162:165], v[214:217], v[38:41]
	v_mfma_f32_16x16x32_bf16 v[34:37], v[182:185], v[214:217], v[34:37]
	v_mfma_f32_16x16x32_bf16 v[22:25], v[162:165], v[222:225], v[22:25]
	v_mfma_f32_16x16x32_bf16 v[18:21], v[182:185], v[222:225], v[18:21]
	v_mfma_f32_16x16x32_bf16 v[6:9], v[162:165], v[230:233], v[6:9]
	v_mfma_f32_16x16x32_bf16 v[2:5], v[182:185], v[230:233], v[2:5]
	v_mfma_f32_16x16x32_bf16 v[54:57], v[178:181], v[210:213], v[54:57]
	v_mfma_f32_16x16x32_bf16 v[50:53], v[186:189], v[210:213], v[50:53]
	v_mfma_f32_16x16x32_bf16 v[38:41], v[178:181], v[218:221], v[38:41]
	v_mfma_f32_16x16x32_bf16 v[34:37], v[186:189], v[218:221], v[34:37]
	v_mfma_f32_16x16x32_bf16 v[22:25], v[178:181], v[226:229], v[22:25]
	v_mfma_f32_16x16x32_bf16 v[18:21], v[186:189], v[226:229], v[18:21]
	v_mfma_f32_16x16x32_bf16 v[6:9], v[178:181], v[234:237], v[6:9]
	v_mfma_f32_16x16x32_bf16 v[2:5], v[186:189], v[234:237], v[2:5]
	s_barrier
	s_setprio 0
	s_add_i32 s48, 0, 0x18000
	v_add_u32_e32 v145, s48, v142
	s_add_i32 s49, 0, 0x1c000
	ds_read_b128 v[146:149], v145
	ds_read_b128 v[150:153], v145 offset:1024
	ds_read_b128 v[154:157], v145 offset:2048
	ds_read_b128 v[158:161], v145 offset:3072
	v_add_u32_e32 v145, s49, v142
	ds_read_b128 v[162:165], v145
	ds_read_b128 v[178:181], v145 offset:1024
	ds_read_b128 v[182:185], v145 offset:2048
	ds_read_b128 v[186:189], v145 offset:3072
	s_add_u32 s46, s66, 0x80000
	s_addc_u32 s47, s67, 0
	s_mov_b32 m0, s74
	v_lshl_add_u64 v[248:249], s[46:47], 0, v[130:131]
	ds_read_b128 v[206:209], v144 offset:32768
	ds_read_b128 v[210:213], v144 offset:33792
	ds_read_b128 v[214:217], v144 offset:34816
	ds_read_b128 v[218:221], v144 offset:35840
	ds_read_b128 v[222:225], v144 offset:36864
	ds_read_b128 v[226:229], v144 offset:37888
	ds_read_b128 v[230:233], v144 offset:38912
	ds_read_b128 v[234:237], v144 offset:39936
	global_load_lds_dwordx4 v[248:249], off
	v_lshl_add_u64 v[248:249], s[46:47], 0, v[132:133]
	s_mov_b32 m0, s75
	s_nop 0
	global_load_lds_dwordx4 v[248:249], off
	s_setprio 1
	s_waitcnt lgkmcnt(7)
	v_mfma_f32_16x16x32_bf16 v[126:129], v[146:149], v[206:209], v[126:129]
	v_mfma_f32_16x16x32_bf16 v[122:125], v[154:157], v[206:209], v[122:125]
	s_waitcnt lgkmcnt(5)
	v_mfma_f32_16x16x32_bf16 v[110:113], v[146:149], v[214:217], v[110:113]
	v_mfma_f32_16x16x32_bf16 v[106:109], v[154:157], v[214:217], v[106:109]
	s_waitcnt vmcnt(8)
	s_waitcnt lgkmcnt(0)
	s_barrier
	v_mfma_f32_16x16x32_bf16 v[94:97], v[146:149], v[222:225], v[94:97]
	v_mfma_f32_16x16x32_bf16 v[90:93], v[154:157], v[222:225], v[90:93]
	v_mfma_f32_16x16x32_bf16 v[78:81], v[146:149], v[230:233], v[78:81]
	v_mfma_f32_16x16x32_bf16 v[74:77], v[154:157], v[230:233], v[74:77]
	v_mfma_f32_16x16x32_bf16 v[126:129], v[150:153], v[210:213], v[126:129]
	v_mfma_f32_16x16x32_bf16 v[122:125], v[158:161], v[210:213], v[122:125]
	v_mfma_f32_16x16x32_bf16 v[110:113], v[150:153], v[218:221], v[110:113]
	v_mfma_f32_16x16x32_bf16 v[106:109], v[158:161], v[218:221], v[106:109]
	v_mfma_f32_16x16x32_bf16 v[94:97], v[150:153], v[226:229], v[94:97]
	v_mfma_f32_16x16x32_bf16 v[90:93], v[158:161], v[226:229], v[90:93]
	v_mfma_f32_16x16x32_bf16 v[78:81], v[150:153], v[234:237], v[78:81]
	v_mfma_f32_16x16x32_bf16 v[74:77], v[158:161], v[234:237], v[74:77]
	s_setprio 0
	s_setprio 1
	v_mfma_f32_16x16x32_bf16 v[118:121], v[162:165], v[206:209], v[118:121]
	v_mfma_f32_16x16x32_bf16 v[114:117], v[182:185], v[206:209], v[114:117]
	v_mfma_f32_16x16x32_bf16 v[102:105], v[162:165], v[214:217], v[102:105]
	v_mfma_f32_16x16x32_bf16 v[98:101], v[182:185], v[214:217], v[98:101]
	v_mfma_f32_16x16x32_bf16 v[86:89], v[162:165], v[222:225], v[86:89]
	v_mfma_f32_16x16x32_bf16 v[82:85], v[182:185], v[222:225], v[82:85]
	v_mfma_f32_16x16x32_bf16 v[70:73], v[162:165], v[230:233], v[70:73]
	v_mfma_f32_16x16x32_bf16 v[66:69], v[182:185], v[230:233], v[66:69]
	v_mfma_f32_16x16x32_bf16 v[118:121], v[178:181], v[210:213], v[118:121]
	v_mfma_f32_16x16x32_bf16 v[114:117], v[186:189], v[210:213], v[114:117]
	v_mfma_f32_16x16x32_bf16 v[102:105], v[178:181], v[218:221], v[102:105]
	v_mfma_f32_16x16x32_bf16 v[98:101], v[186:189], v[218:221], v[98:101]
	v_mfma_f32_16x16x32_bf16 v[86:89], v[178:181], v[226:229], v[86:89]
	v_mfma_f32_16x16x32_bf16 v[82:85], v[186:189], v[226:229], v[82:85]
	v_mfma_f32_16x16x32_bf16 v[70:73], v[178:181], v[234:237], v[70:73]
	v_mfma_f32_16x16x32_bf16 v[66:69], v[186:189], v[234:237], v[66:69]
	s_barrier
	s_setprio 0
	s_add_i32 s46, s48, s72
	v_lshl_add_u64 v[140:141], v[140:141], 0, s[42:43]
	s_mov_b32 m0, s46
	ds_read_b128 v[206:209], v144 offset:49152
	ds_read_b128 v[210:213], v144 offset:50176
	ds_read_b128 v[214:217], v144 offset:51200
	ds_read_b128 v[218:221], v144 offset:52224
	ds_read_b128 v[222:225], v144 offset:53248
	ds_read_b128 v[226:229], v144 offset:54272
	ds_read_b128 v[230:233], v144 offset:55296
	ds_read_b128 v[234:237], v144 offset:56320
	global_load_lds_dwordx4 v[140:141], off
	s_add_i32 m0, s46, 0x2000
	s_add_u32 s46, s60, 0x80080
	v_lshl_add_u64 v[140:141], v[242:243], 0, s[42:43]
	s_addc_u32 s47, s61, 0
	s_add_i32 s48, s49, s72
	global_load_lds_dwordx4 v[140:141], off
	v_lshl_add_u64 v[140:141], s[46:47], 0, v[166:167]
	s_mov_b32 m0, s48
	s_nop 0
	global_load_lds_dwordx4 v[140:141], off
	v_lshl_add_u64 v[140:141], s[46:47], 0, v[134:135]
	s_add_i32 m0, s48, 0x2000
	s_nop 0
	global_load_lds_dwordx4 v[140:141], off
	v_lshl_add_u64 v[140:141], v[244:245], 0, s[42:43]
	s_mov_b32 m0, s76
	s_nop 0
	global_load_lds_dwordx4 v[140:141], off
	v_lshl_add_u64 v[140:141], v[246:247], 0, s[42:43]
	s_mov_b32 m0, s77
	s_nop 0
	global_load_lds_dwordx4 v[140:141], off
	s_setprio 1
	s_waitcnt lgkmcnt(7)
	v_mfma_f32_16x16x32_bf16 v[62:65], v[146:149], v[206:209], v[62:65]
	v_mfma_f32_16x16x32_bf16 v[58:61], v[154:157], v[206:209], v[58:61]
	s_waitcnt lgkmcnt(5)
	v_mfma_f32_16x16x32_bf16 v[46:49], v[146:149], v[214:217], v[46:49]
	v_mfma_f32_16x16x32_bf16 v[42:45], v[154:157], v[214:217], v[42:45]
	s_waitcnt vmcnt(8)
	s_waitcnt lgkmcnt(0)
	s_barrier
	v_mfma_f32_16x16x32_bf16 v[30:33], v[146:149], v[222:225], v[30:33]
	v_mfma_f32_16x16x32_bf16 v[26:29], v[154:157], v[222:225], v[26:29]
	v_mfma_f32_16x16x32_bf16 v[14:17], v[146:149], v[230:233], v[14:17]
	v_mfma_f32_16x16x32_bf16 v[10:13], v[154:157], v[230:233], v[10:13]
	v_mfma_f32_16x16x32_bf16 v[62:65], v[150:153], v[210:213], v[62:65]
	v_mfma_f32_16x16x32_bf16 v[58:61], v[158:161], v[210:213], v[58:61]
	v_mfma_f32_16x16x32_bf16 v[46:49], v[150:153], v[218:221], v[46:49]
	v_mfma_f32_16x16x32_bf16 v[42:45], v[158:161], v[218:221], v[42:45]
	v_mfma_f32_16x16x32_bf16 v[30:33], v[150:153], v[226:229], v[30:33]
	v_mfma_f32_16x16x32_bf16 v[26:29], v[158:161], v[226:229], v[26:29]
	v_mfma_f32_16x16x32_bf16 v[14:17], v[150:153], v[234:237], v[14:17]
	v_mfma_f32_16x16x32_bf16 v[10:13], v[158:161], v[234:237], v[10:13]
	s_setprio 0
	s_setprio 1
	v_mfma_f32_16x16x32_bf16 v[54:57], v[162:165], v[206:209], v[54:57]
	v_mfma_f32_16x16x32_bf16 v[50:53], v[182:185], v[206:209], v[50:53]
	v_mfma_f32_16x16x32_bf16 v[38:41], v[162:165], v[214:217], v[38:41]
	v_mfma_f32_16x16x32_bf16 v[34:37], v[182:185], v[214:217], v[34:37]
	v_mfma_f32_16x16x32_bf16 v[22:25], v[162:165], v[222:225], v[22:25]
	v_mfma_f32_16x16x32_bf16 v[18:21], v[182:185], v[222:225], v[18:21]
	v_mfma_f32_16x16x32_bf16 v[6:9], v[162:165], v[230:233], v[6:9]
	v_mfma_f32_16x16x32_bf16 v[2:5], v[182:185], v[230:233], v[2:5]
	v_mfma_f32_16x16x32_bf16 v[54:57], v[178:181], v[210:213], v[54:57]
	v_mfma_f32_16x16x32_bf16 v[50:53], v[186:189], v[210:213], v[50:53]
	v_mfma_f32_16x16x32_bf16 v[38:41], v[178:181], v[218:221], v[38:41]
	v_mfma_f32_16x16x32_bf16 v[34:37], v[186:189], v[218:221], v[34:37]
	v_mfma_f32_16x16x32_bf16 v[22:25], v[178:181], v[226:229], v[22:25]
	v_mfma_f32_16x16x32_bf16 v[18:21], v[186:189], v[226:229], v[18:21]
	v_mfma_f32_16x16x32_bf16 v[6:9], v[178:181], v[234:237], v[6:9]
	v_mfma_f32_16x16x32_bf16 v[2:5], v[186:189], v[234:237], v[2:5]
	s_barrier
	s_setprio 0
	s_add_i32 s84, s84, 2
	s_add_u32 s64, s64, 0x100
	s_addc_u32 s65, s65, 0
	s_add_u32 s82, s82, 0x100
	s_addc_u32 s83, s83, 0
	s_cmp_gt_u32 s84, 29
	s_cbranch_scc0 .LBB0_1035
	s_and_b64 vcc, exec, s[10:11]
	s_cbranch_vccz .LBB0_1038
	s_barrier

.LBB0_1112:
	s_add_u32 s46, s64, 0xffe00080
	s_addc_u32 s47, s65, -1
	s_add_i32 s48, 0, 0x10000
	s_cmpk_eq_i32 s84, 0x7c
	s_cselect_b32 s67, s19, s47
	s_cselect_b32 s66, s80, s46
	s_cselect_b32 s61, s17, s83
	s_cselect_b32 s60, s81, s82
	s_add_i32 s49, 0, 0x14000
	v_add_u32_e32 v142, s48, v182
	v_add_u32_e32 v164, s49, v182
	ds_read_b128 v[130:133], v142
	ds_read_b128 v[134:137], v142 offset:1024
	ds_read_b128 v[138:141], v142 offset:2048
	ds_read_b128 v[142:145], v142 offset:3072
	ds_read_b128 v[146:149], v164
	ds_read_b128 v[160:163], v164 offset:1024
	ds_read_b128 v[178:181], v164 offset:2048
	ds_read_b128 v[186:189], v164 offset:3072
	v_lshl_add_u64 v[164:165], s[64:65], 0, v[156:157]
	s_add_i32 m0, s63, 0xc000
	ds_read_b128 v[206:209], v184
	ds_read_b128 v[210:213], v184 offset:1024
	ds_read_b128 v[214:217], v184 offset:2048
	ds_read_b128 v[218:221], v184 offset:3072
	ds_read_b128 v[222:225], v184 offset:4096
	ds_read_b128 v[226:229], v184 offset:5120
	ds_read_b128 v[230:233], v184 offset:6144
	ds_read_b128 v[234:237], v184 offset:7168
	global_load_lds_dwordx4 v[164:165], off
	v_lshl_add_u64 v[164:165], s[64:65], 0, v[158:159]
	s_add_i32 m0, s63, 0xe000
	s_nop 0
	global_load_lds_dwordx4 v[164:165], off
	s_setprio 1
	s_waitcnt lgkmcnt(7)
	v_mfma_f32_16x16x32_bf16 v[126:129], v[130:133], v[206:209], v[126:129]
	v_mfma_f32_16x16x32_bf16 v[122:125], v[138:141], v[206:209], v[122:125]
	s_waitcnt lgkmcnt(5)
	v_mfma_f32_16x16x32_bf16 v[118:121], v[130:133], v[214:217], v[118:121]
	v_mfma_f32_16x16x32_bf16 v[114:117], v[138:141], v[214:217], v[114:117]
	s_waitcnt vmcnt(8)
	s_waitcnt lgkmcnt(0)
	s_barrier
	v_mfma_f32_16x16x32_bf16 v[94:97], v[130:133], v[222:225], v[94:97]
	v_mfma_f32_16x16x32_bf16 v[90:93], v[138:141], v[222:225], v[90:93]
	v_mfma_f32_16x16x32_bf16 v[82:85], v[130:133], v[230:233], v[82:85]
	v_mfma_f32_16x16x32_bf16 v[74:77], v[138:141], v[230:233], v[74:77]
	v_mfma_f32_16x16x32_bf16 v[126:129], v[134:137], v[210:213], v[126:129]
	v_mfma_f32_16x16x32_bf16 v[122:125], v[142:145], v[210:213], v[122:125]
	v_mfma_f32_16x16x32_bf16 v[118:121], v[134:137], v[218:221], v[118:121]
	v_mfma_f32_16x16x32_bf16 v[114:117], v[142:145], v[218:221], v[114:117]
	v_mfma_f32_16x16x32_bf16 v[94:97], v[134:137], v[226:229], v[94:97]
	v_mfma_f32_16x16x32_bf16 v[90:93], v[142:145], v[226:229], v[90:93]
	v_mfma_f32_16x16x32_bf16 v[82:85], v[134:137], v[234:237], v[82:85]
	v_mfma_f32_16x16x32_bf16 v[74:77], v[142:145], v[234:237], v[74:77]
	s_setprio 0
	s_setprio 1
	v_mfma_f32_16x16x32_bf16 v[110:113], v[146:149], v[206:209], v[110:113]
	v_mfma_f32_16x16x32_bf16 v[106:109], v[178:181], v[206:209], v[106:109]
	v_mfma_f32_16x16x32_bf16 v[102:105], v[146:149], v[214:217], v[102:105]
	v_mfma_f32_16x16x32_bf16 v[98:101], v[178:181], v[214:217], v[98:101]
	v_mfma_f32_16x16x32_bf16 v[86:89], v[146:149], v[222:225], v[86:89]
	v_mfma_f32_16x16x32_bf16 v[78:81], v[178:181], v[222:225], v[78:81]
	v_mfma_f32_16x16x32_bf16 v[70:73], v[146:149], v[230:233], v[70:73]
	v_mfma_f32_16x16x32_bf16 v[66:69], v[178:181], v[230:233], v[66:69]
	v_mfma_f32_16x16x32_bf16 v[110:113], v[160:163], v[210:213], v[110:113]
	v_mfma_f32_16x16x32_bf16 v[106:109], v[186:189], v[210:213], v[106:109]
	v_mfma_f32_16x16x32_bf16 v[102:105], v[160:163], v[218:221], v[102:105]
	v_mfma_f32_16x16x32_bf16 v[98:101], v[186:189], v[218:221], v[98:101]
	v_mfma_f32_16x16x32_bf16 v[86:89], v[160:163], v[226:229], v[86:89]
	v_mfma_f32_16x16x32_bf16 v[78:81], v[186:189], v[226:229], v[78:81]
	v_mfma_f32_16x16x32_bf16 v[70:73], v[160:163], v[234:237], v[70:73]
	v_mfma_f32_16x16x32_bf16 v[66:69], v[186:189], v[234:237], v[66:69]
	s_barrier
	s_setprio 0
	s_add_i32 s46, s48, s72
	v_lshl_add_u64 v[164:165], s[60:61], 0, v[166:167]
	s_mov_b32 m0, s46
	ds_read_b128 v[206:209], v184 offset:16384
	ds_read_b128 v[210:213], v184 offset:17408
	ds_read_b128 v[214:217], v184 offset:18432
	ds_read_b128 v[218:221], v184 offset:19456
	ds_read_b128 v[222:225], v184 offset:20480
	ds_read_b128 v[226:229], v184 offset:21504
	ds_read_b128 v[230:233], v184 offset:22528
	ds_read_b128 v[234:237], v184 offset:23552
	global_load_lds_dwordx4 v[164:165], off
	s_add_i32 m0, s46, 0x2000
	s_add_u32 s46, s60, 0x200000
	v_lshl_add_u64 v[242:243], s[60:61], 0, v[154:155]
	s_addc_u32 s47, s61, 0
	s_add_i32 s48, s49, s72
	global_load_lds_dwordx4 v[242:243], off
	v_lshl_add_u64 v[244:245], s[46:47], 0, v[166:167]
	s_mov_b32 m0, s48
	v_lshl_add_u64 v[246:247], s[66:67], 0, v[152:153]
	global_load_lds_dwordx4 v[244:245], off
	v_lshl_add_u64 v[244:245], s[46:47], 0, v[154:155]
	s_add_i32 m0, s48, 0x2000
	s_nop 0
	global_load_lds_dwordx4 v[244:245], off
	v_lshl_add_u64 v[244:245], s[66:67], 0, v[150:151]
	s_mov_b32 m0, s63
	s_nop 0
	global_load_lds_dwordx4 v[244:245], off
	s_mov_b32 m0, s73
	s_nop 0
	global_load_lds_dwordx4 v[246:247], off
	s_setprio 1
	s_waitcnt lgkmcnt(7)
	v_mfma_f32_16x16x32_bf16 v[62:65], v[130:133], v[206:209], v[62:65]
	v_mfma_f32_16x16x32_bf16 v[58:61], v[138:141], v[206:209], v[58:61]
	s_waitcnt lgkmcnt(5)
	v_mfma_f32_16x16x32_bf16 v[50:53], v[130:133], v[214:217], v[50:53]
	v_mfma_f32_16x16x32_bf16 v[42:45], v[138:141], v[214:217], v[42:45]
	s_waitcnt vmcnt(8)
	s_waitcnt lgkmcnt(0)
	s_barrier
	v_mfma_f32_16x16x32_bf16 v[34:37], v[130:133], v[222:225], v[34:37]
	v_mfma_f32_16x16x32_bf16 v[26:29], v[138:141], v[222:225], v[26:29]
	v_mfma_f32_16x16x32_bf16 v[18:21], v[130:133], v[230:233], v[18:21]
	v_mfma_f32_16x16x32_bf16 v[10:13], v[138:141], v[230:233], v[10:13]
	v_mfma_f32_16x16x32_bf16 v[62:65], v[134:137], v[210:213], v[62:65]
	v_mfma_f32_16x16x32_bf16 v[58:61], v[142:145], v[210:213], v[58:61]
	v_mfma_f32_16x16x32_bf16 v[50:53], v[134:137], v[218:221], v[50:53]
	v_mfma_f32_16x16x32_bf16 v[42:45], v[142:145], v[218:221], v[42:45]
	v_mfma_f32_16x16x32_bf16 v[34:37], v[134:137], v[226:229], v[34:37]
	v_mfma_f32_16x16x32_bf16 v[26:29], v[142:145], v[226:229], v[26:29]
	v_mfma_f32_16x16x32_bf16 v[18:21], v[134:137], v[234:237], v[18:21]
	v_mfma_f32_16x16x32_bf16 v[10:13], v[142:145], v[234:237], v[10:13]
	s_setprio 0
	s_setprio 1
	v_mfma_f32_16x16x32_bf16 v[54:57], v[146:149], v[206:209], v[54:57]
	v_mfma_f32_16x16x32_bf16 v[46:49], v[178:181], v[206:209], v[46:49]
	v_mfma_f32_16x16x32_bf16 v[38:41], v[146:149], v[214:217], v[38:41]
	v_mfma_f32_16x16x32_bf16 v[30:33], v[178:181], v[214:217], v[30:33]
	v_mfma_f32_16x16x32_bf16 v[22:25], v[146:149], v[222:225], v[22:25]
	v_mfma_f32_16x16x32_bf16 v[14:17], v[178:181], v[222:225], v[14:17]
	v_mfma_f32_16x16x32_bf16 v[6:9], v[146:149], v[230:233], v[6:9]
	v_mfma_f32_16x16x32_bf16 v[2:5], v[178:181], v[230:233], v[2:5]
	v_mfma_f32_16x16x32_bf16 v[54:57], v[160:163], v[210:213], v[54:57]
	v_mfma_f32_16x16x32_bf16 v[46:49], v[186:189], v[210:213], v[46:49]
	v_mfma_f32_16x16x32_bf16 v[38:41], v[160:163], v[218:221], v[38:41]
	v_mfma_f32_16x16x32_bf16 v[30:33], v[186:189], v[218:221], v[30:33]
	v_mfma_f32_16x16x32_bf16 v[22:25], v[160:163], v[226:229], v[22:25]
	v_mfma_f32_16x16x32_bf16 v[14:17], v[186:189], v[226:229], v[14:17]
	v_mfma_f32_16x16x32_bf16 v[6:9], v[160:163], v[234:237], v[6:9]
	v_mfma_f32_16x16x32_bf16 v[2:5], v[186:189], v[234:237], v[2:5]
	s_barrier
	s_setprio 0
	s_add_i32 s48, 0, 0x18000
	s_add_i32 s49, 0, 0x1c000
	v_add_u32_e32 v142, s48, v182
	v_add_u32_e32 v185, s49, v182
	ds_read_b128 v[130:133], v142
	ds_read_b128 v[134:137], v142 offset:1024
	ds_read_b128 v[138:141], v142 offset:2048
	ds_read_b128 v[142:145], v142 offset:3072
	ds_read_b128 v[146:149], v185
	ds_read_b128 v[160:163], v185 offset:1024
	ds_read_b128 v[178:181], v185 offset:2048
	ds_read_b128 v[186:189], v185 offset:3072
	s_add_u32 s46, s66, 0x200000
	s_addc_u32 s47, s67, 0
	s_mov_b32 m0, s74
	v_lshl_add_u64 v[248:249], s[46:47], 0, v[150:151]
	ds_read_b128 v[206:209], v184 offset:32768
	ds_read_b128 v[210:213], v184 offset:33792
	ds_read_b128 v[214:217], v184 offset:34816
	ds_read_b128 v[218:221], v184 offset:35840
	ds_read_b128 v[222:225], v184 offset:36864
	ds_read_b128 v[226:229], v184 offset:37888
	ds_read_b128 v[230:233], v184 offset:38912
	ds_read_b128 v[234:237], v184 offset:39936
	global_load_lds_dwordx4 v[248:249], off
	v_lshl_add_u64 v[248:249], s[46:47], 0, v[152:153]
	s_mov_b32 m0, s75
	s_nop 0
	global_load_lds_dwordx4 v[248:249], off
	s_setprio 1
	s_waitcnt lgkmcnt(7)
	v_mfma_f32_16x16x32_bf16 v[126:129], v[130:133], v[206:209], v[126:129]
	v_mfma_f32_16x16x32_bf16 v[122:125], v[138:141], v[206:209], v[122:125]
	s_waitcnt lgkmcnt(5)
	v_mfma_f32_16x16x32_bf16 v[118:121], v[130:133], v[214:217], v[118:121]
	v_mfma_f32_16x16x32_bf16 v[114:117], v[138:141], v[214:217], v[114:117]
	s_waitcnt vmcnt(8)
	s_waitcnt lgkmcnt(0)
	s_barrier
	v_mfma_f32_16x16x32_bf16 v[94:97], v[130:133], v[222:225], v[94:97]
	v_mfma_f32_16x16x32_bf16 v[90:93], v[138:141], v[222:225], v[90:93]
	v_mfma_f32_16x16x32_bf16 v[82:85], v[130:133], v[230:233], v[82:85]
	v_mfma_f32_16x16x32_bf16 v[74:77], v[138:141], v[230:233], v[74:77]
	v_mfma_f32_16x16x32_bf16 v[126:129], v[134:137], v[210:213], v[126:129]
	v_mfma_f32_16x16x32_bf16 v[122:125], v[142:145], v[210:213], v[122:125]
	v_mfma_f32_16x16x32_bf16 v[118:121], v[134:137], v[218:221], v[118:121]
	v_mfma_f32_16x16x32_bf16 v[114:117], v[142:145], v[218:221], v[114:117]
	v_mfma_f32_16x16x32_bf16 v[94:97], v[134:137], v[226:229], v[94:97]
	v_mfma_f32_16x16x32_bf16 v[90:93], v[142:145], v[226:229], v[90:93]
	v_mfma_f32_16x16x32_bf16 v[82:85], v[134:137], v[234:237], v[82:85]
	v_mfma_f32_16x16x32_bf16 v[74:77], v[142:145], v[234:237], v[74:77]
	s_setprio 0
	s_setprio 1
	v_mfma_f32_16x16x32_bf16 v[110:113], v[146:149], v[206:209], v[110:113]
	v_mfma_f32_16x16x32_bf16 v[106:109], v[178:181], v[206:209], v[106:109]
	v_mfma_f32_16x16x32_bf16 v[102:105], v[146:149], v[214:217], v[102:105]
	v_mfma_f32_16x16x32_bf16 v[98:101], v[178:181], v[214:217], v[98:101]
	v_mfma_f32_16x16x32_bf16 v[86:89], v[146:149], v[222:225], v[86:89]
	v_mfma_f32_16x16x32_bf16 v[78:81], v[178:181], v[222:225], v[78:81]
	v_mfma_f32_16x16x32_bf16 v[70:73], v[146:149], v[230:233], v[70:73]
	v_mfma_f32_16x16x32_bf16 v[66:69], v[178:181], v[230:233], v[66:69]
	v_mfma_f32_16x16x32_bf16 v[110:113], v[160:163], v[210:213], v[110:113]
	v_mfma_f32_16x16x32_bf16 v[106:109], v[186:189], v[210:213], v[106:109]
	v_mfma_f32_16x16x32_bf16 v[102:105], v[160:163], v[218:221], v[102:105]
	v_mfma_f32_16x16x32_bf16 v[98:101], v[186:189], v[218:221], v[98:101]
	v_mfma_f32_16x16x32_bf16 v[86:89], v[160:163], v[226:229], v[86:89]
	v_mfma_f32_16x16x32_bf16 v[78:81], v[186:189], v[226:229], v[78:81]
	v_mfma_f32_16x16x32_bf16 v[70:73], v[160:163], v[234:237], v[70:73]
	v_mfma_f32_16x16x32_bf16 v[66:69], v[186:189], v[234:237], v[66:69]
	s_barrier
	s_setprio 0
	s_add_i32 s46, s48, s72
	v_lshl_add_u64 v[164:165], v[164:165], 0, s[42:43]
	s_mov_b32 m0, s46
	ds_read_b128 v[206:209], v184 offset:49152
	ds_read_b128 v[210:213], v184 offset:50176
	ds_read_b128 v[214:217], v184 offset:51200
	ds_read_b128 v[218:221], v184 offset:52224
	ds_read_b128 v[222:225], v184 offset:53248
	ds_read_b128 v[226:229], v184 offset:54272
	ds_read_b128 v[230:233], v184 offset:55296
	ds_read_b128 v[234:237], v184 offset:56320
	global_load_lds_dwordx4 v[164:165], off
	s_add_i32 m0, s46, 0x2000
	s_add_u32 s46, s60, 0x200080
	v_lshl_add_u64 v[164:165], v[242:243], 0, s[42:43]
	s_addc_u32 s47, s61, 0
	s_add_i32 s48, s49, s72
	global_load_lds_dwordx4 v[164:165], off
	v_lshl_add_u64 v[164:165], s[46:47], 0, v[166:167]
	s_mov_b32 m0, s48
	s_nop 0
	global_load_lds_dwordx4 v[164:165], off
	v_lshl_add_u64 v[164:165], s[46:47], 0, v[154:155]
	s_add_i32 m0, s48, 0x2000
	s_nop 0
	global_load_lds_dwordx4 v[164:165], off
	v_lshl_add_u64 v[164:165], v[244:245], 0, s[42:43]
	s_mov_b32 m0, s76
	s_nop 0
	global_load_lds_dwordx4 v[164:165], off
	v_lshl_add_u64 v[164:165], v[246:247], 0, s[42:43]
	s_mov_b32 m0, s77
	s_nop 0
	global_load_lds_dwordx4 v[164:165], off
	s_setprio 1
	s_waitcnt lgkmcnt(7)
	v_mfma_f32_16x16x32_bf16 v[62:65], v[130:133], v[206:209], v[62:65]
	v_mfma_f32_16x16x32_bf16 v[58:61], v[138:141], v[206:209], v[58:61]
	s_waitcnt lgkmcnt(5)
	v_mfma_f32_16x16x32_bf16 v[50:53], v[130:133], v[214:217], v[50:53]
	v_mfma_f32_16x16x32_bf16 v[42:45], v[138:141], v[214:217], v[42:45]
	s_waitcnt vmcnt(8)
	s_waitcnt lgkmcnt(0)
	s_barrier
	v_mfma_f32_16x16x32_bf16 v[34:37], v[130:133], v[222:225], v[34:37]
	v_mfma_f32_16x16x32_bf16 v[26:29], v[138:141], v[222:225], v[26:29]
	v_mfma_f32_16x16x32_bf16 v[18:21], v[130:133], v[230:233], v[18:21]
	v_mfma_f32_16x16x32_bf16 v[10:13], v[138:141], v[230:233], v[10:13]
	v_mfma_f32_16x16x32_bf16 v[62:65], v[134:137], v[210:213], v[62:65]
	v_mfma_f32_16x16x32_bf16 v[58:61], v[142:145], v[210:213], v[58:61]
	v_mfma_f32_16x16x32_bf16 v[50:53], v[134:137], v[218:221], v[50:53]
	v_mfma_f32_16x16x32_bf16 v[42:45], v[142:145], v[218:221], v[42:45]
	v_mfma_f32_16x16x32_bf16 v[34:37], v[134:137], v[226:229], v[34:37]
	v_mfma_f32_16x16x32_bf16 v[26:29], v[142:145], v[226:229], v[26:29]
	v_mfma_f32_16x16x32_bf16 v[18:21], v[134:137], v[234:237], v[18:21]
	v_mfma_f32_16x16x32_bf16 v[10:13], v[142:145], v[234:237], v[10:13]
	s_setprio 0
	s_setprio 1
	v_mfma_f32_16x16x32_bf16 v[54:57], v[146:149], v[206:209], v[54:57]
	v_mfma_f32_16x16x32_bf16 v[46:49], v[178:181], v[206:209], v[46:49]
	v_mfma_f32_16x16x32_bf16 v[38:41], v[146:149], v[214:217], v[38:41]
	v_mfma_f32_16x16x32_bf16 v[30:33], v[178:181], v[214:217], v[30:33]
	v_mfma_f32_16x16x32_bf16 v[22:25], v[146:149], v[222:225], v[22:25]
	v_mfma_f32_16x16x32_bf16 v[14:17], v[178:181], v[222:225], v[14:17]
	v_mfma_f32_16x16x32_bf16 v[6:9], v[146:149], v[230:233], v[6:9]
	v_mfma_f32_16x16x32_bf16 v[2:5], v[178:181], v[230:233], v[2:5]
	v_mfma_f32_16x16x32_bf16 v[54:57], v[160:163], v[210:213], v[54:57]
	v_mfma_f32_16x16x32_bf16 v[46:49], v[186:189], v[210:213], v[46:49]
	v_mfma_f32_16x16x32_bf16 v[38:41], v[160:163], v[218:221], v[38:41]
	v_mfma_f32_16x16x32_bf16 v[30:33], v[186:189], v[218:221], v[30:33]
	v_mfma_f32_16x16x32_bf16 v[22:25], v[160:163], v[226:229], v[22:25]
	v_mfma_f32_16x16x32_bf16 v[14:17], v[186:189], v[226:229], v[14:17]
	v_mfma_f32_16x16x32_bf16 v[6:9], v[160:163], v[234:237], v[6:9]
	v_mfma_f32_16x16x32_bf16 v[2:5], v[186:189], v[234:237], v[2:5]
	s_barrier
	s_setprio 0
	s_add_i32 s84, s84, 2
	s_add_u32 s64, s64, 0x100
	s_addc_u32 s65, s65, 0
	s_add_u32 s82, s82, 0x100
	s_addc_u32 s83, s83, 0
	s_cmpk_gt_u32 s84, 0x7d
	s_cbranch_scc0 .LBB0_1112
	s_and_b64 vcc, exec, s[12:13]
	s_cbranch_vccz .LBB0_1115
	s_barrier

.LBB0_1138:
	s_add_u32 s46, s62, 0xffe00080
	s_addc_u32 s47, s63, -1
	s_add_i32 s48, 0, 0x10000
	s_cmpk_eq_i32 s82, 0x7c
	s_cselect_b32 s65, s17, s47
	s_cselect_b32 s64, s78, s46
	s_cselect_b32 s61, s13, s81
	s_cselect_b32 s60, s79, s80
	s_add_i32 s49, 0, 0x14000
	v_add_u32_e32 v142, s48, v186
	v_add_u32_e32 v164, s49, v186
	ds_read_b128 v[130:133], v142
	ds_read_b128 v[134:137], v142 offset:1024
	ds_read_b128 v[138:141], v142 offset:2048
	ds_read_b128 v[142:145], v142 offset:3072
	ds_read_b128 v[146:149], v164
	ds_read_b128 v[160:163], v164 offset:1024
	ds_read_b128 v[178:181], v164 offset:2048
	ds_read_b128 v[182:185], v164 offset:3072
	v_lshl_add_u64 v[164:165], s[62:63], 0, v[156:157]
	s_add_i32 m0, s71, 0xc000
	ds_read_b128 v[206:209], v188
	ds_read_b128 v[210:213], v188 offset:1024
	ds_read_b128 v[214:217], v188 offset:2048
	ds_read_b128 v[218:221], v188 offset:3072
	ds_read_b128 v[222:225], v188 offset:4096
	ds_read_b128 v[226:229], v188 offset:5120
	ds_read_b128 v[230:233], v188 offset:6144
	ds_read_b128 v[234:237], v188 offset:7168
	global_load_lds_dwordx4 v[164:165], off
	v_lshl_add_u64 v[164:165], s[62:63], 0, v[158:159]
	s_add_i32 m0, s71, 0xe000
	s_nop 0
	global_load_lds_dwordx4 v[164:165], off
	s_setprio 1
	s_waitcnt lgkmcnt(7)
	v_mfma_f32_16x16x32_bf16 v[126:129], v[130:133], v[206:209], v[126:129]
	v_mfma_f32_16x16x32_bf16 v[122:125], v[138:141], v[206:209], v[122:125]
	s_waitcnt lgkmcnt(5)
	v_mfma_f32_16x16x32_bf16 v[118:121], v[130:133], v[214:217], v[118:121]
	v_mfma_f32_16x16x32_bf16 v[110:113], v[138:141], v[214:217], v[110:113]
	s_waitcnt vmcnt(8)
	s_waitcnt lgkmcnt(0)
	s_barrier
	v_mfma_f32_16x16x32_bf16 v[94:97], v[130:133], v[222:225], v[94:97]
	v_mfma_f32_16x16x32_bf16 v[90:93], v[138:141], v[222:225], v[90:93]
	v_mfma_f32_16x16x32_bf16 v[82:85], v[130:133], v[230:233], v[82:85]
	v_mfma_f32_16x16x32_bf16 v[74:77], v[138:141], v[230:233], v[74:77]
	v_mfma_f32_16x16x32_bf16 v[126:129], v[134:137], v[210:213], v[126:129]
	v_mfma_f32_16x16x32_bf16 v[122:125], v[142:145], v[210:213], v[122:125]
	v_mfma_f32_16x16x32_bf16 v[118:121], v[134:137], v[218:221], v[118:121]
	v_mfma_f32_16x16x32_bf16 v[110:113], v[142:145], v[218:221], v[110:113]
	v_mfma_f32_16x16x32_bf16 v[94:97], v[134:137], v[226:229], v[94:97]
	v_mfma_f32_16x16x32_bf16 v[90:93], v[142:145], v[226:229], v[90:93]
	v_mfma_f32_16x16x32_bf16 v[82:85], v[134:137], v[234:237], v[82:85]
	v_mfma_f32_16x16x32_bf16 v[74:77], v[142:145], v[234:237], v[74:77]
	s_setprio 0
	s_setprio 1
	v_mfma_f32_16x16x32_bf16 v[114:117], v[146:149], v[206:209], v[114:117]
	v_mfma_f32_16x16x32_bf16 v[106:109], v[178:181], v[206:209], v[106:109]
	v_mfma_f32_16x16x32_bf16 v[102:105], v[146:149], v[214:217], v[102:105]
	v_mfma_f32_16x16x32_bf16 v[98:101], v[178:181], v[214:217], v[98:101]
	v_mfma_f32_16x16x32_bf16 v[86:89], v[146:149], v[222:225], v[86:89]
	v_mfma_f32_16x16x32_bf16 v[78:81], v[178:181], v[222:225], v[78:81]
	v_mfma_f32_16x16x32_bf16 v[70:73], v[146:149], v[230:233], v[70:73]
	v_mfma_f32_16x16x32_bf16 v[66:69], v[178:181], v[230:233], v[66:69]
	v_mfma_f32_16x16x32_bf16 v[114:117], v[160:163], v[210:213], v[114:117]
	v_mfma_f32_16x16x32_bf16 v[106:109], v[182:185], v[210:213], v[106:109]
	v_mfma_f32_16x16x32_bf16 v[102:105], v[160:163], v[218:221], v[102:105]
	v_mfma_f32_16x16x32_bf16 v[98:101], v[182:185], v[218:221], v[98:101]
	v_mfma_f32_16x16x32_bf16 v[86:89], v[160:163], v[226:229], v[86:89]
	v_mfma_f32_16x16x32_bf16 v[78:81], v[182:185], v[226:229], v[78:81]
	v_mfma_f32_16x16x32_bf16 v[70:73], v[160:163], v[234:237], v[70:73]
	v_mfma_f32_16x16x32_bf16 v[66:69], v[182:185], v[234:237], v[66:69]
	s_barrier
	s_setprio 0
	s_add_i32 s46, s48, s70
	v_lshl_add_u64 v[164:165], s[60:61], 0, v[166:167]
	s_mov_b32 m0, s46
	ds_read_b128 v[206:209], v188 offset:16384
	ds_read_b128 v[210:213], v188 offset:17408
	ds_read_b128 v[214:217], v188 offset:18432
	ds_read_b128 v[218:221], v188 offset:19456
	ds_read_b128 v[222:225], v188 offset:20480
	ds_read_b128 v[226:229], v188 offset:21504
	ds_read_b128 v[230:233], v188 offset:22528
	ds_read_b128 v[234:237], v188 offset:23552
	global_load_lds_dwordx4 v[164:165], off
	s_add_i32 m0, s46, 0x2000
	s_add_u32 s46, s60, 0x200000
	v_lshl_add_u64 v[242:243], s[60:61], 0, v[154:155]
	s_addc_u32 s47, s61, 0
	s_add_i32 s48, s49, s70
	global_load_lds_dwordx4 v[242:243], off
	v_lshl_add_u64 v[244:245], s[46:47], 0, v[166:167]
	s_mov_b32 m0, s48
	v_lshl_add_u64 v[246:247], s[64:65], 0, v[152:153]
	global_load_lds_dwordx4 v[244:245], off
	v_lshl_add_u64 v[244:245], s[46:47], 0, v[154:155]
	s_add_i32 m0, s48, 0x2000
	s_nop 0
	global_load_lds_dwordx4 v[244:245], off
	v_lshl_add_u64 v[244:245], s[64:65], 0, v[150:151]
	s_mov_b32 m0, s71
	s_nop 0
	global_load_lds_dwordx4 v[244:245], off
	s_mov_b32 m0, s72
	s_nop 0
	global_load_lds_dwordx4 v[246:247], off
	s_setprio 1
	s_waitcnt lgkmcnt(7)
	v_mfma_f32_16x16x32_bf16 v[62:65], v[130:133], v[206:209], v[62:65]
	v_mfma_f32_16x16x32_bf16 v[58:61], v[138:141], v[206:209], v[58:61]
	s_waitcnt lgkmcnt(5)
	v_mfma_f32_16x16x32_bf16 v[50:53], v[130:133], v[214:217], v[50:53]
	v_mfma_f32_16x16x32_bf16 v[42:45], v[138:141], v[214:217], v[42:45]
	s_waitcnt vmcnt(8)
	s_waitcnt lgkmcnt(0)
	s_barrier
	v_mfma_f32_16x16x32_bf16 v[34:37], v[130:133], v[222:225], v[34:37]
	v_mfma_f32_16x16x32_bf16 v[26:29], v[138:141], v[222:225], v[26:29]
	v_mfma_f32_16x16x32_bf16 v[18:21], v[130:133], v[230:233], v[18:21]
	v_mfma_f32_16x16x32_bf16 v[10:13], v[138:141], v[230:233], v[10:13]
	v_mfma_f32_16x16x32_bf16 v[62:65], v[134:137], v[210:213], v[62:65]
	v_mfma_f32_16x16x32_bf16 v[58:61], v[142:145], v[210:213], v[58:61]
	v_mfma_f32_16x16x32_bf16 v[50:53], v[134:137], v[218:221], v[50:53]
	v_mfma_f32_16x16x32_bf16 v[42:45], v[142:145], v[218:221], v[42:45]
	v_mfma_f32_16x16x32_bf16 v[34:37], v[134:137], v[226:229], v[34:37]
	v_mfma_f32_16x16x32_bf16 v[26:29], v[142:145], v[226:229], v[26:29]
	v_mfma_f32_16x16x32_bf16 v[18:21], v[134:137], v[234:237], v[18:21]
	v_mfma_f32_16x16x32_bf16 v[10:13], v[142:145], v[234:237], v[10:13]
	s_setprio 0
	s_setprio 1
	v_mfma_f32_16x16x32_bf16 v[54:57], v[146:149], v[206:209], v[54:57]
	v_mfma_f32_16x16x32_bf16 v[46:49], v[178:181], v[206:209], v[46:49]
	v_mfma_f32_16x16x32_bf16 v[38:41], v[146:149], v[214:217], v[38:41]
	v_mfma_f32_16x16x32_bf16 v[30:33], v[178:181], v[214:217], v[30:33]
	v_mfma_f32_16x16x32_bf16 v[22:25], v[146:149], v[222:225], v[22:25]
	v_mfma_f32_16x16x32_bf16 v[14:17], v[178:181], v[222:225], v[14:17]
	v_mfma_f32_16x16x32_bf16 v[6:9], v[146:149], v[230:233], v[6:9]
	v_mfma_f32_16x16x32_bf16 v[2:5], v[178:181], v[230:233], v[2:5]
	v_mfma_f32_16x16x32_bf16 v[54:57], v[160:163], v[210:213], v[54:57]
	v_mfma_f32_16x16x32_bf16 v[46:49], v[182:185], v[210:213], v[46:49]
	v_mfma_f32_16x16x32_bf16 v[38:41], v[160:163], v[218:221], v[38:41]
	v_mfma_f32_16x16x32_bf16 v[30:33], v[182:185], v[218:221], v[30:33]
	v_mfma_f32_16x16x32_bf16 v[22:25], v[160:163], v[226:229], v[22:25]
	v_mfma_f32_16x16x32_bf16 v[14:17], v[182:185], v[226:229], v[14:17]
	v_mfma_f32_16x16x32_bf16 v[6:9], v[160:163], v[234:237], v[6:9]
	v_mfma_f32_16x16x32_bf16 v[2:5], v[182:185], v[234:237], v[2:5]
	s_barrier
	s_setprio 0
	s_add_i32 s48, 0, 0x18000
	s_add_i32 s49, 0, 0x1c000
	v_add_u32_e32 v142, s48, v186
	v_add_u32_e32 v182, s49, v186
	ds_read_b128 v[130:133], v142
	ds_read_b128 v[134:137], v142 offset:1024
	ds_read_b128 v[138:141], v142 offset:2048
	ds_read_b128 v[142:145], v142 offset:3072
	ds_read_b128 v[146:149], v182
	ds_read_b128 v[160:163], v182 offset:1024
	ds_read_b128 v[178:181], v182 offset:2048
	ds_read_b128 v[182:185], v182 offset:3072
	s_add_u32 s46, s64, 0x200000
	s_addc_u32 s47, s65, 0
	s_mov_b32 m0, s73
	v_lshl_add_u64 v[248:249], s[46:47], 0, v[150:151]
	ds_read_b128 v[206:209], v188 offset:32768
	ds_read_b128 v[210:213], v188 offset:33792
	ds_read_b128 v[214:217], v188 offset:34816
	ds_read_b128 v[218:221], v188 offset:35840
	ds_read_b128 v[222:225], v188 offset:36864
	ds_read_b128 v[226:229], v188 offset:37888
	ds_read_b128 v[230:233], v188 offset:38912
	ds_read_b128 v[234:237], v188 offset:39936
	global_load_lds_dwordx4 v[248:249], off
	v_lshl_add_u64 v[248:249], s[46:47], 0, v[152:153]
	s_mov_b32 m0, s74
	s_nop 0
	global_load_lds_dwordx4 v[248:249], off
	s_setprio 1
	s_waitcnt lgkmcnt(7)
	v_mfma_f32_16x16x32_bf16 v[126:129], v[130:133], v[206:209], v[126:129]
	v_mfma_f32_16x16x32_bf16 v[122:125], v[138:141], v[206:209], v[122:125]
	s_waitcnt lgkmcnt(5)
	v_mfma_f32_16x16x32_bf16 v[118:121], v[130:133], v[214:217], v[118:121]
	v_mfma_f32_16x16x32_bf16 v[110:113], v[138:141], v[214:217], v[110:113]
	s_waitcnt vmcnt(8)
	s_waitcnt lgkmcnt(0)
	s_barrier
	v_mfma_f32_16x16x32_bf16 v[94:97], v[130:133], v[222:225], v[94:97]
	v_mfma_f32_16x16x32_bf16 v[90:93], v[138:141], v[222:225], v[90:93]
	v_mfma_f32_16x16x32_bf16 v[82:85], v[130:133], v[230:233], v[82:85]
	v_mfma_f32_16x16x32_bf16 v[74:77], v[138:141], v[230:233], v[74:77]
	v_mfma_f32_16x16x32_bf16 v[126:129], v[134:137], v[210:213], v[126:129]
	v_mfma_f32_16x16x32_bf16 v[122:125], v[142:145], v[210:213], v[122:125]
	v_mfma_f32_16x16x32_bf16 v[118:121], v[134:137], v[218:221], v[118:121]
	v_mfma_f32_16x16x32_bf16 v[110:113], v[142:145], v[218:221], v[110:113]
	v_mfma_f32_16x16x32_bf16 v[94:97], v[134:137], v[226:229], v[94:97]
	v_mfma_f32_16x16x32_bf16 v[90:93], v[142:145], v[226:229], v[90:93]
	v_mfma_f32_16x16x32_bf16 v[82:85], v[134:137], v[234:237], v[82:85]
	v_mfma_f32_16x16x32_bf16 v[74:77], v[142:145], v[234:237], v[74:77]
	s_setprio 0
	s_setprio 1
	v_mfma_f32_16x16x32_bf16 v[114:117], v[146:149], v[206:209], v[114:117]
	v_mfma_f32_16x16x32_bf16 v[106:109], v[178:181], v[206:209], v[106:109]
	v_mfma_f32_16x16x32_bf16 v[102:105], v[146:149], v[214:217], v[102:105]
	v_mfma_f32_16x16x32_bf16 v[98:101], v[178:181], v[214:217], v[98:101]
	v_mfma_f32_16x16x32_bf16 v[86:89], v[146:149], v[222:225], v[86:89]
	v_mfma_f32_16x16x32_bf16 v[78:81], v[178:181], v[222:225], v[78:81]
	v_mfma_f32_16x16x32_bf16 v[70:73], v[146:149], v[230:233], v[70:73]
	v_mfma_f32_16x16x32_bf16 v[66:69], v[178:181], v[230:233], v[66:69]
	v_mfma_f32_16x16x32_bf16 v[114:117], v[160:163], v[210:213], v[114:117]
	v_mfma_f32_16x16x32_bf16 v[106:109], v[182:185], v[210:213], v[106:109]
	v_mfma_f32_16x16x32_bf16 v[102:105], v[160:163], v[218:221], v[102:105]
	v_mfma_f32_16x16x32_bf16 v[98:101], v[182:185], v[218:221], v[98:101]
	v_mfma_f32_16x16x32_bf16 v[86:89], v[160:163], v[226:229], v[86:89]
	v_mfma_f32_16x16x32_bf16 v[78:81], v[182:185], v[226:229], v[78:81]
	v_mfma_f32_16x16x32_bf16 v[70:73], v[160:163], v[234:237], v[70:73]
	v_mfma_f32_16x16x32_bf16 v[66:69], v[182:185], v[234:237], v[66:69]
	s_barrier
	s_setprio 0
	s_add_i32 s46, s48, s70
	v_lshl_add_u64 v[164:165], v[164:165], 0, s[42:43]
	s_mov_b32 m0, s46
	ds_read_b128 v[206:209], v188 offset:49152
	ds_read_b128 v[210:213], v188 offset:50176
	ds_read_b128 v[214:217], v188 offset:51200
	ds_read_b128 v[218:221], v188 offset:52224
	ds_read_b128 v[222:225], v188 offset:53248
	ds_read_b128 v[226:229], v188 offset:54272
	ds_read_b128 v[230:233], v188 offset:55296
	ds_read_b128 v[234:237], v188 offset:56320
	global_load_lds_dwordx4 v[164:165], off
	s_add_i32 m0, s46, 0x2000
	s_add_u32 s46, s60, 0x200080
	v_lshl_add_u64 v[164:165], v[242:243], 0, s[42:43]
	s_addc_u32 s47, s61, 0
	s_add_i32 s48, s49, s70
	global_load_lds_dwordx4 v[164:165], off
	v_lshl_add_u64 v[164:165], s[46:47], 0, v[166:167]
	s_mov_b32 m0, s48
	s_nop 0
	global_load_lds_dwordx4 v[164:165], off
	v_lshl_add_u64 v[164:165], s[46:47], 0, v[154:155]
	s_add_i32 m0, s48, 0x2000
	s_nop 0
	global_load_lds_dwordx4 v[164:165], off
	v_lshl_add_u64 v[164:165], v[244:245], 0, s[42:43]
	s_mov_b32 m0, s75
	s_nop 0
	global_load_lds_dwordx4 v[164:165], off
	v_lshl_add_u64 v[164:165], v[246:247], 0, s[42:43]
	s_mov_b32 m0, s76
	s_nop 0
	global_load_lds_dwordx4 v[164:165], off
	s_setprio 1
	s_waitcnt lgkmcnt(7)
	v_mfma_f32_16x16x32_bf16 v[62:65], v[130:133], v[206:209], v[62:65]
	v_mfma_f32_16x16x32_bf16 v[58:61], v[138:141], v[206:209], v[58:61]
	s_waitcnt lgkmcnt(5)
	v_mfma_f32_16x16x32_bf16 v[50:53], v[130:133], v[214:217], v[50:53]
	v_mfma_f32_16x16x32_bf16 v[42:45], v[138:141], v[214:217], v[42:45]
	s_waitcnt vmcnt(8)
	s_waitcnt lgkmcnt(0)
	s_barrier
	v_mfma_f32_16x16x32_bf16 v[34:37], v[130:133], v[222:225], v[34:37]
	v_mfma_f32_16x16x32_bf16 v[26:29], v[138:141], v[222:225], v[26:29]
	v_mfma_f32_16x16x32_bf16 v[18:21], v[130:133], v[230:233], v[18:21]
	v_mfma_f32_16x16x32_bf16 v[10:13], v[138:141], v[230:233], v[10:13]
	v_mfma_f32_16x16x32_bf16 v[62:65], v[134:137], v[210:213], v[62:65]
	v_mfma_f32_16x16x32_bf16 v[58:61], v[142:145], v[210:213], v[58:61]
	v_mfma_f32_16x16x32_bf16 v[50:53], v[134:137], v[218:221], v[50:53]
	v_mfma_f32_16x16x32_bf16 v[42:45], v[142:145], v[218:221], v[42:45]
	v_mfma_f32_16x16x32_bf16 v[34:37], v[134:137], v[226:229], v[34:37]
	v_mfma_f32_16x16x32_bf16 v[26:29], v[142:145], v[226:229], v[26:29]
	v_mfma_f32_16x16x32_bf16 v[18:21], v[134:137], v[234:237], v[18:21]
	v_mfma_f32_16x16x32_bf16 v[10:13], v[142:145], v[234:237], v[10:13]
	s_setprio 0
	s_setprio 1
	v_mfma_f32_16x16x32_bf16 v[54:57], v[146:149], v[206:209], v[54:57]
	v_mfma_f32_16x16x32_bf16 v[46:49], v[178:181], v[206:209], v[46:49]
	v_mfma_f32_16x16x32_bf16 v[38:41], v[146:149], v[214:217], v[38:41]
	v_mfma_f32_16x16x32_bf16 v[30:33], v[178:181], v[214:217], v[30:33]
	v_mfma_f32_16x16x32_bf16 v[22:25], v[146:149], v[222:225], v[22:25]
	v_mfma_f32_16x16x32_bf16 v[14:17], v[178:181], v[222:225], v[14:17]
	v_mfma_f32_16x16x32_bf16 v[6:9], v[146:149], v[230:233], v[6:9]
	v_mfma_f32_16x16x32_bf16 v[2:5], v[178:181], v[230:233], v[2:5]
	v_mfma_f32_16x16x32_bf16 v[54:57], v[160:163], v[210:213], v[54:57]
	v_mfma_f32_16x16x32_bf16 v[46:49], v[182:185], v[210:213], v[46:49]
	v_mfma_f32_16x16x32_bf16 v[38:41], v[160:163], v[218:221], v[38:41]
	v_mfma_f32_16x16x32_bf16 v[30:33], v[182:185], v[218:221], v[30:33]
	v_mfma_f32_16x16x32_bf16 v[22:25], v[160:163], v[226:229], v[22:25]
	v_mfma_f32_16x16x32_bf16 v[14:17], v[182:185], v[226:229], v[14:17]
	v_mfma_f32_16x16x32_bf16 v[6:9], v[160:163], v[234:237], v[6:9]
	v_mfma_f32_16x16x32_bf16 v[2:5], v[182:185], v[234:237], v[2:5]
	s_barrier
	s_setprio 0
	s_add_i32 s82, s82, 2
	s_add_u32 s62, s62, 0x100
	s_addc_u32 s63, s63, 0
	s_add_u32 s80, s80, 0x100
	s_addc_u32 s81, s81, 0
	s_cmpk_gt_u32 s82, 0x7d
	s_cbranch_scc0 .LBB0_1138
	s_and_b64 vcc, exec, s[10:11]
	s_cbranch_vccz .LBB0_1141
	s_barrier
